# residual-GEMM full-unit epilogue: workgroups without a split-K piece pause (s_sleep 30) between row groups so the workgroups that still have a piece to run finish their memory-bound epilogue first
# speedup vs baseline: 1.0084x; 1.0084x over previous
.Lls1_8_noflush:
	s_waitcnt lgkmcnt(11)
	v_mul_f32_e32 v10, v74, v10
	v_mul_f32_e32 v11, v75, v11
	v_mul_f32_e32 v12, v76, v12
	ds_read_b128 v[28:31], v0 offset:2560
	v_mul_f32_e32 v13, v77, v13
	v_fmac_f32_e32 v10, v32, v60
	v_fmac_f32_e32 v11, v33, v60
	ds_read_b128 v[46:49], v0 offset:3584
	v_mul_f32_e32 v102, v50, v10
	v_fmac_f32_e32 v12, v34, v60
	v_fmac_f32_e32 v102, v51, v11
	ds_read_b128 v[70:73], v0 offset:5888
	v_fmac_f32_e32 v13, v35, v60
	v_fmac_f32_e32 v102, v52, v12
	v_fmac_f32_e32 v102, v53, v13
	ds_read_b32 v58, v1 offset:4416
	ds_write_b32 v107, v102 offset:10496
	s_waitcnt lgkmcnt(11)
	v_mul_f32_e32 v10, v62, v10
	v_mul_f32_e32 v11, v63, v11
	v_mul_f32_e32 v12, v64, v12
	s_waitcnt vmcnt(11)
	v_mul_f32_e32 v13, v65, v13
	v_fmac_f32_e32 v10, v20, v54
	v_fmac_f32_e32 v11, v21, v54
	v_lshlrev_b32_e32 v94, 16, v86
	v_mul_f32_e32 v61, v38, v10
	v_fmac_f32_e32 v12, v22, v54
	v_fmac_f32_e32 v61, v39, v11
	v_and_b32_e32 v95, 0xffff0000, v86
	v_fmac_f32_e32 v13, v23, v54
	v_fmac_f32_e32 v61, v40, v12
	v_fmac_f32_e32 v61, v41, v13
	v_lshlrev_b32_e32 v96, 16, v87
	ds_write_b32 v107, v61 offset:10752
	ds_read_b128 v[32:35], v0 offset:2688
	ds_read_b128 v[50:53], v0 offset:3712
	ds_read_b128 v[74:77], v0 offset:6016
	ds_read_b32 v60, v1 offset:4448
	s_waitcnt lgkmcnt(11)
	v_mul_f32_e32 v10, v66, v10
	v_mul_f32_e32 v11, v67, v11
	v_mul_f32_e32 v12, v68, v12
	v_and_b32_e32 v97, 0xffff0000, v87
	v_mul_f32_e32 v13, v69, v13
	v_fmac_f32_e32 v10, v24, v56
	v_fmac_f32_e32 v11, v25, v56
	ds_write_b128 v2, v[94:97] offset:0
	v_mul_f32_e32 v102, v42, v10
	v_fmac_f32_e32 v12, v26, v56
	v_fmac_f32_e32 v102, v43, v11
	v_lshlrev_b32_e32 v98, 16, v88
	v_fmac_f32_e32 v13, v27, v56
	v_fmac_f32_e32 v102, v44, v12
	v_fmac_f32_e32 v102, v45, v13
	v_and_b32_e32 v99, 0xffff0000, v88
	ds_write_b32 v107, v102 offset:11008
	ds_read_b128 v[20:23], v0 offset:2816
	ds_read_b128 v[38:41], v0 offset:3840
	ds_read_b128 v[62:65], v0 offset:6144
	ds_read_b32 v54, v1 offset:4480
	s_waitcnt lgkmcnt(12)
	v_mul_f32_e32 v10, v70, v10
	v_mul_f32_e32 v11, v71, v11
	v_mul_f32_e32 v12, v72, v12
	v_lshlrev_b32_e32 v100, 16, v89
	v_mul_f32_e32 v13, v73, v13
	v_fmac_f32_e32 v10, v28, v58
	v_fmac_f32_e32 v11, v29, v58
	v_and_b32_e32 v101, 0xffff0000, v89
	v_mul_f32_e32 v61, v46, v10
	v_fmac_f32_e32 v12, v30, v58
	v_fmac_f32_e32 v61, v47, v11
	ds_write_b128 v2, v[98:101] offset:16
	v_fmac_f32_e32 v13, v31, v58
	v_fmac_f32_e32 v61, v48, v12
	v_fmac_f32_e32 v61, v49, v13
	s_waitcnt vmcnt(10)
	ds_write_b32 v107, v61 offset:11264
	ds_read_b128 v[24:27], v0 offset:2944
	ds_read_b128 v[42:45], v0 offset:3968
	ds_read_b128 v[66:69], v0 offset:6272
	ds_read_b32 v56, v1 offset:4512
	s_waitcnt lgkmcnt(12)
	v_mul_f32_e32 v10, v74, v10
	v_mul_f32_e32 v11, v75, v11
	v_mul_f32_e32 v12, v76, v12
	v_lshlrev_b32_e32 v57, 16, v57
	v_mul_f32_e32 v13, v77, v13
	v_fmac_f32_e32 v10, v32, v60
	v_fmac_f32_e32 v11, v33, v60
	s_nop 0
	v_mul_f32_e32 v102, v50, v10
	v_fmac_f32_e32 v12, v34, v60
	v_fmac_f32_e32 v102, v51, v11
	ds_write_b32 v4, v57 offset:2048
	v_fmac_f32_e32 v13, v35, v60
	v_fmac_f32_e32 v102, v52, v12
	v_fmac_f32_e32 v102, v53, v13
	ds_read_b128 v[28:31], v0 offset:3072
	ds_write_b32 v107, v102 offset:11520
	ds_read_b128 v[46:49], v0 offset:4096
	ds_read_b128 v[70:73], v0 offset:6400
	ds_read_b32 v58, v1 offset:4544
	s_waitcnt lgkmcnt(12)
	v_mul_f32_e32 v10, v62, v10
	v_mul_f32_e32 v11, v63, v11
	v_mul_f32_e32 v12, v64, v12
	global_load_dwordx4 v[86:89], v5, s[94:95]
	global_load_ushort v57, v6, s[94:95]
	v_add_u32_e32 v5, v5, v9
	v_add_u32_e32 v6, 0x10000, v6
	v_mul_f32_e32 v13, v65, v13
	v_fmac_f32_e32 v10, v20, v54
	v_fmac_f32_e32 v11, v21, v54
	s_add_i32 m0, s29, 0x1200
	s_nop 0
	global_load_lds_dwordx4 v8, s[94:95]
	v_add_u32_e32 v8, 0x3180, v8
	v_mul_f32_e32 v61, v38, v10
	v_fmac_f32_e32 v12, v22, v54
	v_fmac_f32_e32 v61, v39, v11
	ds_read_b128 v[114:117], v112 offset:8704
	v_fmac_f32_e32 v13, v23, v54
	v_fmac_f32_e32 v61, v40, v12
	v_fmac_f32_e32 v61, v41, v13
	ds_read_b128 v[118:121], v113 offset:8704
	ds_write_b32 v107, v61 offset:11776
	ds_read_b128 v[32:35], v0 offset:3200
	ds_read_b128 v[50:53], v0 offset:4224
	ds_read_b128 v[74:77], v0 offset:6528
	ds_read_b32 v60, v1 offset:4576
	s_waitcnt lgkmcnt(13)
	v_mul_f32_e32 v10, v66, v10
	v_mul_f32_e32 v11, v67, v11
	v_mul_f32_e32 v12, v68, v12
	ds_read_b128 v[20:23], v0 offset:0
	v_mul_f32_e32 v13, v69, v13
	v_fmac_f32_e32 v10, v24, v56
	v_fmac_f32_e32 v11, v25, v56
	ds_read_b128 v[38:41], v0 offset:1024
	v_mul_f32_e32 v102, v42, v10
	v_fmac_f32_e32 v12, v26, v56
	v_fmac_f32_e32 v102, v43, v11
	s_waitcnt vmcnt(6)
	v_fmac_f32_e32 v13, v27, v56
	v_fmac_f32_e32 v102, v44, v12
	v_fmac_f32_e32 v102, v45, v13
	ds_read_b128 v[62:65], v0 offset:6656
	ds_write_b32 v107, v102 offset:12032
	ds_read_b32 v54, v1 offset:2048
	s_waitcnt lgkmcnt(12)
	v_mul_f32_e32 v10, v70, v10
	v_mul_f32_e32 v11, v71, v11
	v_mul_f32_e32 v12, v72, v12
	s_waitcnt lgkmcnt(10)
	v_mul_f32_e32 v13, v73, v13
	v_fmac_f32_e32 v10, v28, v58
	v_fmac_f32_e32 v11, v29, v58
	v_add_f32_e32 v114, v114, v118
	v_mul_f32_e32 v61, v46, v10
	v_fmac_f32_e32 v12, v30, v58
	v_fmac_f32_e32 v61, v47, v11
	v_add_f32_e32 v115, v115, v119
	v_fmac_f32_e32 v13, v31, v58
	v_fmac_f32_e32 v61, v48, v12
	v_fmac_f32_e32 v61, v49, v13
	v_add_f32_e32 v116, v116, v120
	ds_write_b32 v107, v61 offset:12288
	ds_read_b128 v[24:27], v0 offset:128
	ds_read_b128 v[42:45], v0 offset:1152
	ds_read_b128 v[66:69], v0 offset:6784
	ds_read_b32 v56, v1 offset:2080
	v_add_f32_e32 v117, v117, v121
	v_add_f32_e32 v114, v114, v115
	v_add_f32_e32 v116, v116, v117
	v_add_f32_e32 v114, v114, v116
	v_cvt_pk_bf16_f32 v19, v114, v114
	ds_write_b16 v105, v19 offset:13312
	s_waitcnt lgkmcnt(11)
	v_mul_f32_e32 v10, v74, v10
	v_mul_f32_e32 v11, v75, v11
	v_mul_f32_e32 v12, v76, v12
	ds_read_b128 v[28:31], v0 offset:256
	v_mul_f32_e32 v13, v77, v13
	v_fmac_f32_e32 v10, v32, v60
	v_fmac_f32_e32 v11, v33, v60
	ds_read_b128 v[46:49], v0 offset:1280
	v_mul_f32_e32 v102, v50, v10
	v_fmac_f32_e32 v12, v34, v60
	v_fmac_f32_e32 v102, v51, v11
	ds_read_b128 v[70:73], v0 offset:6912
	v_fmac_f32_e32 v13, v35, v60
	v_fmac_f32_e32 v102, v52, v12
	v_fmac_f32_e32 v102, v53, v13
	ds_read_b32 v58, v1 offset:2112
	ds_write_b32 v107, v102 offset:12544
	s_waitcnt lgkmcnt(11)
	v_mul_f32_e32 v10, v62, v10
	v_mul_f32_e32 v11, v63, v11
	v_mul_f32_e32 v12, v64, v12
	s_waitcnt vmcnt(11)
	v_mul_f32_e32 v13, v65, v13
	v_fmac_f32_e32 v10, v20, v54
	v_fmac_f32_e32 v11, v21, v54
	v_lshlrev_b32_e32 v94, 16, v90
	v_mul_f32_e32 v61, v38, v10
	v_fmac_f32_e32 v12, v22, v54
	v_fmac_f32_e32 v61, v39, v11
	v_and_b32_e32 v95, 0xffff0000, v90
	v_fmac_f32_e32 v13, v23, v54
	v_fmac_f32_e32 v61, v40, v12
	v_fmac_f32_e32 v61, v41, v13
	v_lshlrev_b32_e32 v96, 16, v91
	ds_write_b32 v107, v61 offset:8704
	ds_read_b128 v[32:35], v0 offset:384
	ds_read_b128 v[50:53], v0 offset:1408
	ds_read_b128 v[74:77], v0 offset:7040
	ds_read_b32 v60, v1 offset:2144
	s_waitcnt lgkmcnt(11)
	v_mul_f32_e32 v10, v66, v10
	v_mul_f32_e32 v11, v67, v11
	v_mul_f32_e32 v12, v68, v12
	v_and_b32_e32 v97, 0xffff0000, v91
	v_mul_f32_e32 v13, v69, v13
	v_fmac_f32_e32 v10, v24, v56
	v_fmac_f32_e32 v11, v25, v56
	ds_write_b128 v2, v[94:97] offset:2304
	v_mul_f32_e32 v102, v42, v10
	v_fmac_f32_e32 v12, v26, v56
	v_fmac_f32_e32 v102, v43, v11
	v_lshlrev_b32_e32 v98, 16, v92
	v_fmac_f32_e32 v13, v27, v56
	v_fmac_f32_e32 v102, v44, v12
	v_fmac_f32_e32 v102, v45, v13
	v_and_b32_e32 v99, 0xffff0000, v92
	ds_write_b32 v107, v102 offset:8960
	ds_read_b128 v[20:23], v0 offset:512
	ds_read_b128 v[38:41], v0 offset:1536
	ds_read_b128 v[62:65], v0 offset:7168
	ds_read_b32 v54, v1 offset:2176
	s_waitcnt lgkmcnt(12)
	v_mul_f32_e32 v10, v70, v10
	v_mul_f32_e32 v11, v71, v11
	v_mul_f32_e32 v12, v72, v12
	v_lshlrev_b32_e32 v100, 16, v93
	v_mul_f32_e32 v13, v73, v13
	v_fmac_f32_e32 v10, v28, v58
	v_fmac_f32_e32 v11, v29, v58
	v_and_b32_e32 v101, 0xffff0000, v93
	v_mul_f32_e32 v61, v46, v10
	v_fmac_f32_e32 v12, v30, v58
	v_fmac_f32_e32 v61, v47, v11
	ds_write_b128 v2, v[98:101] offset:2320
	v_fmac_f32_e32 v13, v31, v58
	v_fmac_f32_e32 v61, v48, v12
	v_fmac_f32_e32 v61, v49, v13
	s_waitcnt vmcnt(10)
	ds_write_b32 v107, v61 offset:9216
	ds_read_b128 v[24:27], v0 offset:640
	ds_read_b128 v[42:45], v0 offset:1664
	ds_read_b128 v[66:69], v0 offset:7296
	ds_read_b32 v56, v1 offset:2208
	s_waitcnt lgkmcnt(12)
	v_mul_f32_e32 v10, v74, v10
	v_mul_f32_e32 v11, v75, v11
	v_mul_f32_e32 v12, v76, v12
	v_lshlrev_b32_e32 v59, 16, v59
	v_mul_f32_e32 v13, v77, v13
	v_fmac_f32_e32 v10, v32, v60
	v_fmac_f32_e32 v11, v33, v60
	s_nop 0
	v_mul_f32_e32 v102, v50, v10
	v_fmac_f32_e32 v12, v34, v60
	v_fmac_f32_e32 v102, v51, v11
	ds_write_b32 v4, v59 offset:4352
	v_fmac_f32_e32 v13, v35, v60
	v_fmac_f32_e32 v102, v52, v12
	v_fmac_f32_e32 v102, v53, v13
	ds_read_b128 v[28:31], v0 offset:768
	ds_write_b32 v107, v102 offset:9472
	ds_read_b128 v[46:49], v0 offset:1792
	ds_read_b128 v[70:73], v0 offset:7424
	ds_read_b32 v58, v1 offset:2240
	s_waitcnt lgkmcnt(12)
	v_mul_f32_e32 v10, v62, v10
	v_mul_f32_e32 v11, v63, v11
	v_mul_f32_e32 v12, v64, v12
	global_load_dwordx4 v[90:93], v5, s[94:95]
	global_load_ushort v59, v6, s[94:95]
	v_add_u32_e32 v5, v5, v9
	v_add_u32_e32 v6, 0x10000, v6
	v_mul_f32_e32 v13, v65, v13
	v_fmac_f32_e32 v10, v20, v54
	v_fmac_f32_e32 v11, v21, v54
	s_add_i32 m0, s29, 0x1600
	s_nop 0
	global_load_lds_dwordx4 v8, s[94:95]
	v_add_u32_e32 v8, 0x3180, v8
	v_mul_f32_e32 v61, v38, v10
	v_fmac_f32_e32 v12, v22, v54
	v_fmac_f32_e32 v61, v39, v11
	ds_read_b128 v[114:117], v112 offset:10752
	v_fmac_f32_e32 v13, v23, v54
	v_fmac_f32_e32 v61, v40, v12
	v_fmac_f32_e32 v61, v41, v13
	ds_read_b128 v[118:121], v113 offset:10752
	ds_write_b32 v107, v61 offset:9728
	ds_read_b128 v[32:35], v0 offset:896
	ds_read_b128 v[50:53], v0 offset:1920
	ds_read_b128 v[74:77], v0 offset:7552
	ds_read_b32 v60, v1 offset:2272
	s_waitcnt lgkmcnt(13)
	v_mul_f32_e32 v10, v66, v10
	v_mul_f32_e32 v11, v67, v11
	v_mul_f32_e32 v12, v68, v12
	ds_read_b128 v[20:23], v0 offset:2304
	v_mul_f32_e32 v13, v69, v13
	v_fmac_f32_e32 v10, v24, v56
	v_fmac_f32_e32 v11, v25, v56
	ds_read_b128 v[38:41], v0 offset:3328
	v_mul_f32_e32 v102, v42, v10
	v_fmac_f32_e32 v12, v26, v56
	v_fmac_f32_e32 v102, v43, v11
	s_waitcnt vmcnt(6)
	v_fmac_f32_e32 v13, v27, v56
	v_fmac_f32_e32 v102, v44, v12
	v_fmac_f32_e32 v102, v45, v13
	ds_read_b128 v[62:65], v0 offset:7680
	ds_write_b32 v107, v102 offset:9984
	ds_read_b32 v54, v1 offset:4352
	s_waitcnt lgkmcnt(12)
	v_mul_f32_e32 v10, v70, v10
	v_mul_f32_e32 v11, v71, v11
	v_mul_f32_e32 v12, v72, v12
	s_waitcnt lgkmcnt(10)
	v_mul_f32_e32 v13, v73, v13
	v_fmac_f32_e32 v10, v28, v58
	v_fmac_f32_e32 v11, v29, v58
	v_add_f32_e32 v114, v114, v118
	v_mul_f32_e32 v61, v46, v10
	v_fmac_f32_e32 v12, v30, v58
	v_fmac_f32_e32 v61, v47, v11
	v_add_f32_e32 v115, v115, v119
	v_fmac_f32_e32 v13, v31, v58
	v_fmac_f32_e32 v61, v48, v12
	v_fmac_f32_e32 v61, v49, v13
	v_add_f32_e32 v116, v116, v120
	ds_write_b32 v107, v61 offset:10240
	ds_read_b128 v[24:27], v0 offset:2432
	ds_read_b128 v[42:45], v0 offset:3456
	ds_read_b128 v[66:69], v0 offset:7808
	ds_read_b32 v56, v1 offset:4384
	v_add_f32_e32 v117, v117, v121
	v_add_f32_e32 v114, v114, v115
	v_add_f32_e32 v116, v116, v117
	v_add_f32_e32 v114, v114, v116
	v_cvt_pk_bf16_f32 v19, v114, v114
	ds_write_b16 v105, v19 offset:13440
	s_waitcnt lgkmcnt(11)
	v_mul_f32_e32 v10, v74, v10
	v_mul_f32_e32 v11, v75, v11
	v_mul_f32_e32 v12, v76, v12
	ds_read_b128 v[28:31], v0 offset:2560
	v_mul_f32_e32 v13, v77, v13
	v_fmac_f32_e32 v10, v32, v60
	v_fmac_f32_e32 v11, v33, v60
	ds_read_b128 v[46:49], v0 offset:3584
	v_mul_f32_e32 v102, v50, v10
	v_fmac_f32_e32 v12, v34, v60
	v_fmac_f32_e32 v102, v51, v11
	ds_read_b128 v[70:73], v0 offset:7936
	v_fmac_f32_e32 v13, v35, v60
	v_fmac_f32_e32 v102, v52, v12
	v_fmac_f32_e32 v102, v53, v13
	ds_read_b32 v58, v1 offset:4416
	ds_write_b32 v107, v102 offset:10496
	s_waitcnt lgkmcnt(11)
	v_mul_f32_e32 v10, v62, v10
	v_mul_f32_e32 v11, v63, v11
	v_mul_f32_e32 v12, v64, v12
	s_waitcnt vmcnt(11)
	v_mul_f32_e32 v13, v65, v13
	v_fmac_f32_e32 v10, v20, v54
	v_fmac_f32_e32 v11, v21, v54
	v_lshlrev_b32_e32 v94, 16, v78
	v_mul_f32_e32 v61, v38, v10
	v_fmac_f32_e32 v12, v22, v54
	v_fmac_f32_e32 v61, v39, v11
	v_and_b32_e32 v95, 0xffff0000, v78
	v_fmac_f32_e32 v13, v23, v54
	v_fmac_f32_e32 v61, v40, v12
	v_fmac_f32_e32 v61, v41, v13
	v_lshlrev_b32_e32 v96, 16, v79
	ds_write_b32 v107, v61 offset:10752
	ds_read_b128 v[32:35], v0 offset:2688
	ds_read_b128 v[50:53], v0 offset:3712
	ds_read_b128 v[74:77], v0 offset:8064
	ds_read_b32 v60, v1 offset:4448
	s_waitcnt lgkmcnt(11)
	v_mul_f32_e32 v10, v66, v10
	v_mul_f32_e32 v11, v67, v11
	v_mul_f32_e32 v12, v68, v12
	v_and_b32_e32 v97, 0xffff0000, v79
	v_mul_f32_e32 v13, v69, v13
	v_fmac_f32_e32 v10, v24, v56
	v_fmac_f32_e32 v11, v25, v56
	ds_write_b128 v2, v[94:97] offset:0
	v_mul_f32_e32 v102, v42, v10
	v_fmac_f32_e32 v12, v26, v56
	v_fmac_f32_e32 v102, v43, v11
	v_lshlrev_b32_e32 v98, 16, v80
	v_fmac_f32_e32 v13, v27, v56
	v_fmac_f32_e32 v102, v44, v12
	v_fmac_f32_e32 v102, v45, v13
	v_and_b32_e32 v99, 0xffff0000, v80
	ds_write_b32 v107, v102 offset:11008
	ds_read_b128 v[20:23], v0 offset:2816
	ds_read_b128 v[38:41], v0 offset:3840
	ds_read_b128 v[62:65], v0 offset:8192
	ds_read_b32 v54, v1 offset:4480
	s_waitcnt lgkmcnt(12)
	v_mul_f32_e32 v10, v70, v10
	v_mul_f32_e32 v11, v71, v11
	v_mul_f32_e32 v12, v72, v12
	v_lshlrev_b32_e32 v100, 16, v81
	v_mul_f32_e32 v13, v73, v13
	v_fmac_f32_e32 v10, v28, v58
	v_fmac_f32_e32 v11, v29, v58
	v_and_b32_e32 v101, 0xffff0000, v81
	v_mul_f32_e32 v61, v46, v10
	v_fmac_f32_e32 v12, v30, v58
	v_fmac_f32_e32 v61, v47, v11
	ds_write_b128 v2, v[98:101] offset:16
	v_fmac_f32_e32 v13, v31, v58
	v_fmac_f32_e32 v61, v48, v12
	v_fmac_f32_e32 v61, v49, v13
	s_waitcnt vmcnt(10)
	ds_write_b32 v107, v61 offset:11264
	ds_read_b128 v[24:27], v0 offset:2944
	ds_read_b128 v[42:45], v0 offset:3968
	ds_read_b128 v[66:69], v0 offset:8320
	ds_read_b32 v56, v1 offset:4512
	s_waitcnt lgkmcnt(12)
	v_mul_f32_e32 v10, v74, v10
	v_mul_f32_e32 v11, v75, v11
	v_mul_f32_e32 v12, v76, v12
	v_lshlrev_b32_e32 v36, 16, v36
	v_mul_f32_e32 v13, v77, v13
	v_fmac_f32_e32 v10, v32, v60
	v_fmac_f32_e32 v11, v33, v60
	s_nop 0
	v_mul_f32_e32 v102, v50, v10
	v_fmac_f32_e32 v12, v34, v60
	v_fmac_f32_e32 v102, v51, v11
	ds_write_b32 v4, v36 offset:2048
	v_fmac_f32_e32 v13, v35, v60
	v_fmac_f32_e32 v102, v52, v12
	v_fmac_f32_e32 v102, v53, v13
	ds_read_b128 v[28:31], v0 offset:3072
	ds_write_b32 v107, v102 offset:11520
	ds_read_b128 v[46:49], v0 offset:4096
	ds_read_b128 v[70:73], v0 offset:8448
	ds_read_b32 v58, v1 offset:4544
	s_waitcnt lgkmcnt(12)
	v_mul_f32_e32 v10, v62, v10
	v_mul_f32_e32 v11, v63, v11
	v_mul_f32_e32 v12, v64, v12
	global_load_dwordx4 v[78:81], v5, s[94:95]
	global_load_ushort v36, v6, s[94:95]
	v_add_u32_e32 v5, v5, v9
	v_add_u32_e32 v6, 0x10000, v6
	v_mul_f32_e32 v13, v65, v13
	v_fmac_f32_e32 v10, v20, v54
	v_fmac_f32_e32 v11, v21, v54
	s_add_i32 m0, s29, 0x1a00
	s_nop 0
	global_load_lds_dwordx4 v8, s[94:95]
	v_add_u32_e32 v8, 0x3180, v8
	v_mul_f32_e32 v61, v38, v10
	v_fmac_f32_e32 v12, v22, v54
	v_fmac_f32_e32 v61, v39, v11
	ds_read_b128 v[114:117], v112 offset:8704
	v_fmac_f32_e32 v13, v23, v54
	v_fmac_f32_e32 v61, v40, v12
	v_fmac_f32_e32 v61, v41, v13
	ds_read_b128 v[118:121], v113 offset:8704
	ds_write_b32 v107, v61 offset:11776
	ds_read_b128 v[32:35], v0 offset:3200
	ds_read_b128 v[50:53], v0 offset:4224
	ds_read_b128 v[74:77], v0 offset:8576
	ds_read_b32 v60, v1 offset:4576
	s_waitcnt lgkmcnt(13)
	v_mul_f32_e32 v10, v66, v10
	v_mul_f32_e32 v11, v67, v11
	v_mul_f32_e32 v12, v68, v12
	ds_read_b128 v[20:23], v0 offset:0
	v_mul_f32_e32 v13, v69, v13
	v_fmac_f32_e32 v10, v24, v56
	v_fmac_f32_e32 v11, v25, v56
	ds_read_b128 v[38:41], v0 offset:1024
	v_mul_f32_e32 v102, v42, v10
	v_fmac_f32_e32 v12, v26, v56
	v_fmac_f32_e32 v102, v43, v11
	s_waitcnt vmcnt(6)
	v_fmac_f32_e32 v13, v27, v56
	v_fmac_f32_e32 v102, v44, v12
	v_fmac_f32_e32 v102, v45, v13
	ds_read_b128 v[62:65], v0 offset:4608
	ds_write_b32 v107, v102 offset:12032
	ds_read_b32 v54, v1 offset:2048
	s_waitcnt lgkmcnt(12)
	v_mul_f32_e32 v10, v70, v10
	v_mul_f32_e32 v11, v71, v11
	v_mul_f32_e32 v12, v72, v12
	s_waitcnt lgkmcnt(10)
	v_mul_f32_e32 v13, v73, v13
	v_fmac_f32_e32 v10, v28, v58
	v_fmac_f32_e32 v11, v29, v58
	v_add_f32_e32 v114, v114, v118
	v_mul_f32_e32 v61, v46, v10
	v_fmac_f32_e32 v12, v30, v58
	v_fmac_f32_e32 v61, v47, v11
	v_add_f32_e32 v115, v115, v119
	v_fmac_f32_e32 v13, v31, v58
	v_fmac_f32_e32 v61, v48, v12
	v_fmac_f32_e32 v61, v49, v13
	v_add_f32_e32 v116, v116, v120
	ds_write_b32 v107, v61 offset:12288
	ds_read_b128 v[24:27], v0 offset:128
	ds_read_b128 v[42:45], v0 offset:1152
	ds_read_b128 v[66:69], v0 offset:4736
	ds_read_b32 v56, v1 offset:2080
	v_add_f32_e32 v117, v117, v121
	v_add_f32_e32 v114, v114, v115
	v_add_f32_e32 v116, v116, v117
	v_add_f32_e32 v114, v114, v116
	v_cvt_pk_bf16_f32 v19, v114, v114
	ds_write_b16 v105, v19 offset:13568
	s_waitcnt lgkmcnt(11)
	v_mul_f32_e32 v10, v74, v10
	v_mul_f32_e32 v11, v75, v11
	v_mul_f32_e32 v12, v76, v12
	ds_read_b128 v[28:31], v0 offset:256
	v_mul_f32_e32 v13, v77, v13
	v_fmac_f32_e32 v10, v32, v60
	v_fmac_f32_e32 v11, v33, v60
	ds_read_b128 v[46:49], v0 offset:1280
	v_mul_f32_e32 v102, v50, v10
	v_fmac_f32_e32 v12, v34, v60
	v_fmac_f32_e32 v102, v51, v11
	ds_read_b128 v[70:73], v0 offset:4864
	v_fmac_f32_e32 v13, v35, v60
	v_fmac_f32_e32 v102, v52, v12
	v_fmac_f32_e32 v102, v53, v13
	ds_read_b32 v58, v1 offset:2112
	ds_write_b32 v107, v102 offset:12544
	s_sub_u32 s12, s12, 1
	s_cmp_lg_u32 s12, 0
	s_cbranch_scc1 .Lls1_8_loop
	ds_read_b128 v[114:117], v112 offset:10752
	ds_read_b128 v[118:121], v113 offset:10752
	s_waitcnt lgkmcnt(0)
	v_add_f32_e32 v114, v114, v118
	v_add_f32_e32 v115, v115, v119
	v_add_f32_e32 v116, v116, v120
	v_add_f32_e32 v117, v117, v121
	v_add_f32_e32 v114, v114, v115
	v_add_f32_e32 v116, v116, v117
	v_add_f32_e32 v114, v114, v116
	v_cvt_pk_bf16_f32 v19, v114, v114
	ds_write_b16 v105, v19 offset:13696
	s_waitcnt lgkmcnt(0)
	ds_read_b128 v[108:111], v106 offset:13312
	s_waitcnt lgkmcnt(0)
	global_store_dwordx4 v7, v[108:111], s[94:95]
	v_add_u32_e32 v7, 0x20000, v7
	s_nop 0
	ds_read_b128 v[108:111], v106 offset:14336
	s_waitcnt lgkmcnt(0)
	global_store_dwordx4 v7, v[108:111], s[94:95]
	v_add_u32_e32 v7, 0x20000, v7
	s_nop 0
	ds_read_b128 v[108:111], v106 offset:15360
	s_waitcnt lgkmcnt(0)
	global_store_dwordx4 v7, v[108:111], s[94:95]
	v_add_u32_e32 v7, 0x20000, v7
	s_nop 0
	ds_read_b128 v[108:111], v106 offset:16384
	s_waitcnt lgkmcnt(0)
	global_store_dwordx4 v7, v[108:111], s[94:95]
	v_add_u32_e32 v7, 0x20000, v7
	s_nop 0
	ds_read_b128 v[108:111], v106 offset:17408
	s_waitcnt lgkmcnt(0)
	global_store_dwordx4 v7, v[108:111], s[94:95]
	v_add_u32_e32 v7, 0x20000, v7
	s_nop 0
	ds_read_b128 v[108:111], v106 offset:18432
	s_waitcnt lgkmcnt(0)
	global_store_dwordx4 v7, v[108:111], s[94:95]
	v_add_u32_e32 v7, 0x20000, v7
	s_nop 0
	ds_read_b128 v[108:111], v106 offset:19456
	s_waitcnt lgkmcnt(0)
	global_store_dwordx4 v7, v[108:111], s[94:95]
	v_add_u32_e32 v7, 0x20000, v7
	s_nop 0
	ds_read_b128 v[108:111], v106 offset:20480
	s_waitcnt lgkmcnt(0)
	global_store_dwordx4 v7, v[108:111], s[94:95]
	v_add_u32_e32 v7, 0x20000, v7
	s_nop 0
	global_store_dword v104, v10, s[26:27] offset:0
	global_store_dword v104, v11, s[26:27] offset:256
	global_store_dword v104, v12, s[26:27] offset:512
	global_store_dword v104, v13, s[26:27] offset:768
	s_waitcnt vmcnt(0) lgkmcnt(0)
	s_setprio 0
	s_branch .Lls_done
.Lisl_LBB0_1541:
	s_branch .LBB0_1541
.Lls_done:
	s_lshl_b32 s1, s0, 2
	s_lshr_b32 s1, 0x73652140, s1
	s_and_b32 s1, s1, 7
	s_lshl_b32 s1, s1, 6
	v_and_b32_e32 v37, 63, v196
	v_or_b32_e32 v37, s1, v37
	v_readlane_b32 s8, v253, 27
	v_readfirstlane_b32 s0, v37
	s_ashr_i32 s12, s0, 6
	v_readlane_b32 s10, v253, 29
	v_readlane_b32 s11, v253, 30
	s_lshl_b32 s3, s12, 8
	v_mov_b32_e32 v0, s10
	v_mov_b32_e32 v1, s11
	v_writelane_b32 v255, s3, 21
	s_add_i32 s3, s3, s2
	s_cmpk_gt_i32 s3, 0x3ff
	v_readfirstlane_b32 s0, v0
	v_readfirstlane_b32 s1, v1
	v_mov_b32_e32 v0, s94
	v_mov_b32_e32 v1, s95
	s_cselect_b64 s[94:95], -1, 0
	s_cmp_gt_i32 s12, 4
	s_cselect_b64 s[78:79], -1, 0
	s_add_i32 s70, s3, 0xfffffb00
	s_ashr_i32 s6, s3, 8
	s_cmp_eq_u32 s6, 2
	s_cselect_b32 s7, 2, 1
	s_cmp_lg_u32 s6, 1
	s_cselect_b32 s6, s7, 0
	s_cmpk_gt_u32 s3, 0xff
	s_cselect_b32 s28, s6, 3
	s_add_u32 s2, s0, 0x5da4000
	v_writelane_b32 v255, s2, 22
	s_addc_u32 s2, s1, 0
	v_writelane_b32 v255, s2, 23
	s_add_u32 s2, s0, 0x55a4000
	v_writelane_b32 v255, s2, 24
	v_readfirstlane_b32 s86, v0
	s_addc_u32 s2, s1, 0
	v_readfirstlane_b32 s87, v1
	s_add_u32 s85, s86, 0x8400000
	s_addc_u32 s37, s87, 0
	s_add_u32 s67, s86, 0x13e00000
	s_addc_u32 s66, s87, 0
	s_add_u32 s5, s0, 0x45a4000
	s_addc_u32 s4, s1, 0
	s_add_u32 s91, s86, 0x10800000
	s_addc_u32 s90, s87, 0
	v_writelane_b32 v255, s2, 25
	s_add_u32 s2, s86, 0x6300000
	v_writelane_b32 v255, s2, 26
	s_addc_u32 s2, s87, 0
	v_writelane_b32 v255, s2, 27
	s_add_u32 s2, s0, 0x6da4000
	v_writelane_b32 v255, s2, 28
	s_addc_u32 s2, s1, 0
	s_mul_i32 s3, s12, 0x6c00
	v_writelane_b32 v255, s2, 29
	s_add_i32 s59, s3, 0
	v_writelane_b32 v255, s12, 30
	s_add_u32 s2, s0, 0x4380000
	v_lshrrev_b32_e32 v0, 3, v37
	v_writelane_b32 v255, s2, 31
	s_addc_u32 s2, s1, 0
	v_and_b32_e32 v39, 6, v0
	v_lshrrev_b32_e32 v0, 2, v37
	v_writelane_b32 v255, s2, 32
	s_add_u32 s2, s0, 0x4300000
	v_and_b32_e32 v41, 12, v0
	v_bfe_u32 v0, v37, 2, 4
	v_and_b32_e32 v2, 3, v37
	v_lshlrev_b32_e32 v3, 12, v37
	v_writelane_b32 v255, s2, 33
	s_addc_u32 s2, s1, 0
	v_and_b32_e32 v48, 0xf000, v3
	v_mul_u32_u24_e32 v3, 0x110, v0
	v_lshlrev_b32_e32 v4, 6, v2
	v_writelane_b32 v255, s2, 34
	s_add_u32 s2, s0, 0x4200000
	v_and_b32_e32 v49, 7, v37
	v_add3_u32 v53, s59, v3, v4
	v_mov_b32_e32 v3, s59
	s_movk_i32 s3, 0x90
	v_writelane_b32 v255, s2, 35
	s_addc_u32 s2, s1, 0
	v_and_b32_e32 v33, 63, v37
	v_and_b32_e32 v1, 15, v37
	v_mul_hi_u32_u24_e32 v45, 0xd00, v0
	v_mul_u32_u24_e32 v44, 0xd00, v0
	v_mul_hi_u32_u24_e32 v47, 0x630, v0
	v_mul_u32_u24_e32 v46, 0x630, v0
	v_lshl_add_u32 v101, v49, 5, s59
	v_lshlrev_b32_e32 v54, 13, v0
	v_mad_u32_u24 v3, v0, s3, v3
	v_lshlrev_b32_e32 v0, 4, v49
	v_writelane_b32 v255, s2, 36
	s_add_u32 s0, s0, 0x4480000
	v_readlane_b32 s9, v253, 28
	v_bfe_u32 v32, v37, 3, 3
	v_lshlrev_b32_e32 v42, 4, v2
	v_lshlrev_b32_e32 v52, 3, v2
	v_lshlrev_b32_e32 v4, 5, v2
	v_sub_u32_e32 v113, v101, v0
	v_writelane_b32 v255, s0, 37
	s_addc_u32 s0, s1, 0
	v_mul_u32_u24_e32 v0, 0x680, v1
	v_mul_u32_u24_e32 v2, 0x18c, v1
	v_lshlrev_b32_e32 v5, 4, v33
	v_lshlrev_b32_e32 v60, 3, v1
	v_mov_b32_e32 v61, v145
	s_mov_b32 s92, 0
	v_lshlrev_b32_e32 v34, 2, v1
	v_mov_b32_e32 v35, v145
	v_lshlrev_b32_e32 v36, 8, v1
	v_cmp_eq_u32_e64 s[6:7], 0, v1
	v_lshlrev_b32_e32 v38, 1, v1
	v_lshlrev_b32_e32 v40, 7, v1
	v_bfe_u32 v43, v37, 4, 2
	v_cmp_gt_u32_e64 s[8:9], 16, v33
	v_lshl_add_u32 v99, v33, 5, s59
	v_lshl_add_u32 v111, v32, 2, s59
	v_cmp_eq_u32_e64 s[10:11], 0, v49
	v_cmp_eq_u32_e64 s[12:13], 1, v49
	v_cmp_eq_u32_e64 s[14:15], 2, v49
	v_cmp_eq_u32_e64 s[16:17], 3, v49
	v_cmp_eq_u32_e64 s[18:19], 4, v49
	v_cmp_eq_u32_e64 s[20:21], 5, v49
	v_cmp_eq_u32_e64 s[22:23], 6, v49
	v_cmp_eq_u32_e64 s[24:25], 7, v49
	v_lshlrev_b32_e32 v50, 11, v49
	v_mov_b32_e32 v51, v145
	v_mov_b32_e32 v55, v145
	v_lshlrev_b32_e32 v56, 10, v49
	v_mov_b32_e32 v57, v145
	v_mov_b32_e32 v58, v44
	v_mov_b32_e32 v59, v145
	v_writelane_b32 v255, s0, 38
	v_lshlrev_b32_e32 v62, 4, v1
	v_mov_b32_e32 v63, v145
	v_lshl_add_u64 v[64:65], s[86:87], 0, v[60:61]
	v_lshlrev_b32_e32 v66, 1, v0
	v_lshlrev_b32_e32 v68, 2, v2
	v_add_u32_e32 v117, v3, v4
	v_add_u32_e32 v119, s59, v5
	v_readlane_b32 s2, v253, 10
	s_branch .LBB0_684

.LBB0_1163:
	s_ashr_i32 s17, s54, 3
	s_mul_hi_i32 s19, s17, 0x9000
	s_mul_i32 s17, s17, 0x9000
	s_add_u32 s26, s10, s17
	s_addc_u32 s27, s11, s19
	v_lshl_add_u64 v[162:163], s[26:27], 0, v[160:161]
	global_load_dwordx4 v[64:67], v[162:163], off
	v_readlane_b32 s26, v255, 5
	v_readlane_b32 s27, v255, 6
	s_lshl_b32 s17, s54, 8
	v_add_u32_e32 v194, s17, v151
	v_lshl_add_u64 v[166:167], s[26:27], 0, v[160:161]
	v_readlane_b32 s26, v255, 9
	v_readlane_b32 s27, v255, 10
	v_ashrrev_i32_e32 v195, 31, v194
	v_lshl_add_u64 v[212:213], v[194:195], 3, s[12:13]
	v_lshl_add_u64 v[168:169], s[26:27], 0, v[160:161]
	v_lshlrev_b64 v[214:215], 12, v[194:195]
	v_lshl_add_u64 v[214:215], s[0:1], 0, v[214:215]
	v_lshl_add_u64 v[214:215], v[214:215], 0, v[160:161]
	s_waitcnt vmcnt(0)
	v_pk_add_f32 v[178:179], v[66:67], 1.0 op_sel_hi:[1,0]
	v_pk_add_f32 v[180:181], v[64:65], 1.0 op_sel_hi:[1,0]
	global_load_dwordx4 v[84:87], v[166:167], off
	global_load_dwordx4 v[64:67], v[168:169], off
	s_waitcnt vmcnt(0)
	v_pk_mul_f32 v[190:191], v[66:67], s[58:59] op_sel_hi:[1,0]
	v_pk_mul_f32 v[192:193], v[64:65], s[58:59] op_sel_hi:[1,0]
	global_load_dwordx4 v[64:67], v[162:163], off offset:64
	s_waitcnt vmcnt(0)
	v_pk_add_f32 v[174:175], v[66:67], 1.0 op_sel_hi:[1,0]
	v_pk_add_f32 v[176:177], v[64:65], 1.0 op_sel_hi:[1,0]
	global_load_dwordx4 v[72:75], v[166:167], off offset:64
	global_load_dwordx4 v[64:67], v[168:169], off offset:64
	s_waitcnt vmcnt(0)
	v_pk_mul_f32 v[186:187], v[66:67], s[58:59] op_sel_hi:[1,0]
	v_pk_mul_f32 v[188:189], v[64:65], s[58:59] op_sel_hi:[1,0]
	global_load_dwordx4 v[64:67], v[162:163], off offset:512
	s_waitcnt vmcnt(0)
	v_pk_add_f32 v[170:171], v[66:67], 1.0 op_sel_hi:[1,0]
	v_pk_add_f32 v[172:173], v[64:65], 1.0 op_sel_hi:[1,0]
	global_load_dwordx4 v[68:71], v[166:167], off offset:512
	global_load_dwordx4 v[64:67], v[168:169], off offset:512
	s_waitcnt vmcnt(0)
	v_pk_mul_f32 v[182:183], v[66:67], s[58:59] op_sel_hi:[1,0]
	v_pk_mul_f32 v[184:185], v[64:65], s[58:59] op_sel_hi:[1,0]
	global_load_dwordx4 v[64:67], v[162:163], off offset:576
	s_waitcnt vmcnt(0)
	v_pk_add_f32 v[162:163], v[66:67], 1.0 op_sel_hi:[1,0]
	v_pk_add_f32 v[164:165], v[64:65], 1.0 op_sel_hi:[1,0]
	global_load_dwordx4 v[64:67], v[166:167], off offset:576
	global_load_dwordx4 v[232:235], v[168:169], off offset:576
	s_waitcnt vmcnt(0)
	v_pk_mul_f32 v[166:167], v[234:235], s[58:59] op_sel_hi:[1,0]
	global_load_dwordx2 v[212:213], v[212:213], off
	v_pk_mul_f32 v[168:169], v[232:233], s[58:59] op_sel_hi:[1,0]
	global_load_dwordx4 v[232:235], v[214:215], off
	global_load_dwordx4 v[236:239], v[214:215], off offset:64
	global_load_dwordx4 v[240:243], v[214:215], off offset:512
	global_load_dwordx4 v[244:247], v[214:215], off offset:576
	s_waitcnt vmcnt(4)
	v_mul_f32_e32 v216, 0x3fb504f3, v213
	s_waitcnt vmcnt(3)
	v_sub_f32_e32 v219, v233, v212
	v_sub_f32_e32 v218, v232, v212
	v_sub_f32_e32 v233, v235, v212
	v_sub_f32_e32 v232, v234, v212
	v_pk_mul_f32 v[232:233], v[232:233], v[216:217] op_sel_hi:[1,0]
	v_pk_mul_f32 v[218:219], v[218:219], v[216:217] op_sel_hi:[1,0]
	v_pk_fma_f32 v[232:233], v[86:87], v[232:233], v[190:191]
	v_pk_fma_f32 v[218:219], v[84:85], v[218:219], v[192:193]
	v_pk_fma_f32 v[142:143], v[142:143], v[178:179], v[232:233]
	v_pk_fma_f32 v[140:141], v[140:141], v[180:181], v[218:219]
	global_store_dwordx4 v[214:215], v[140:143], off
	s_waitcnt vmcnt(3)
	s_nop 0
	v_sub_f32_e32 v141, v237, v212
	v_sub_f32_e32 v140, v236, v212
	v_sub_f32_e32 v143, v239, v212
	v_sub_f32_e32 v142, v238, v212
	v_pk_mul_f32 v[142:143], v[142:143], v[216:217] op_sel_hi:[1,0]
	v_pk_mul_f32 v[140:141], v[140:141], v[216:217] op_sel_hi:[1,0]
	v_pk_fma_f32 v[142:143], v[74:75], v[142:143], v[186:187]
	v_pk_fma_f32 v[140:141], v[72:73], v[140:141], v[188:189]
	v_pk_fma_f32 v[138:139], v[138:139], v[174:175], v[142:143]
	v_pk_fma_f32 v[136:137], v[136:137], v[176:177], v[140:141]
	global_store_dwordx4 v[214:215], v[136:139], off offset:64
	s_waitcnt vmcnt(3)
	s_nop 0
	v_sub_f32_e32 v137, v241, v212
	v_sub_f32_e32 v136, v240, v212
	v_sub_f32_e32 v139, v243, v212
	v_sub_f32_e32 v138, v242, v212
	v_pk_mul_f32 v[138:139], v[216:217], v[138:139] op_sel_hi:[0,1]
	v_pk_mul_f32 v[136:137], v[216:217], v[136:137] op_sel_hi:[0,1]
	v_pk_fma_f32 v[136:137], v[68:69], v[136:137], v[184:185]
	v_pk_fma_f32 v[138:139], v[70:71], v[138:139], v[182:183]
	v_pk_fma_f32 v[132:133], v[132:133], v[172:173], v[136:137]
	v_pk_fma_f32 v[134:135], v[134:135], v[170:171], v[138:139]
	global_store_dwordx4 v[214:215], v[132:135], off offset:512
	s_waitcnt vmcnt(3)
	s_nop 0
	v_sub_f32_e32 v133, v245, v212
	v_sub_f32_e32 v132, v244, v212
	v_sub_f32_e32 v135, v247, v212
	v_sub_f32_e32 v134, v246, v212
	v_pk_mul_f32 v[134:135], v[216:217], v[134:135] op_sel_hi:[0,1]
	v_pk_mul_f32 v[132:133], v[216:217], v[132:133] op_sel_hi:[0,1]
	v_pk_fma_f32 v[132:133], v[64:65], v[132:133], v[168:169]
	v_pk_fma_f32 v[134:135], v[66:67], v[134:135], v[166:167]
	v_pk_fma_f32 v[128:129], v[128:129], v[164:165], v[132:133]
	v_pk_fma_f32 v[130:131], v[130:131], v[162:163], v[134:135]
	global_store_dwordx4 v[214:215], v[128:131], off offset:576
	s_and_b64 vcc, exec, s[6:7]
	s_cbranch_vccnz .Lmy_epi_w0
	s_sleep 30
.Lmy_epi_w0:
	s_nop 1
	v_add_u32_e32 v128, s17, v226
	v_ashrrev_i32_e32 v129, 31, v128
	v_lshl_add_u64 v[130:131], v[128:129], 3, s[12:13]
	global_load_dwordx2 v[212:213], v[130:131], off
	v_lshlrev_b64 v[128:129], 12, v[128:129]
	v_lshl_add_u64 v[128:129], s[0:1], 0, v[128:129]
	v_lshl_add_u64 v[214:215], v[128:129], 0, v[160:161]
	global_load_dwordx4 v[128:131], v[214:215], off
	global_load_dwordx4 v[132:135], v[214:215], off offset:64
	global_load_dwordx4 v[136:139], v[214:215], off offset:512
	global_load_dwordx4 v[140:143], v[214:215], off offset:576
	s_waitcnt vmcnt(4)
	v_mul_f32_e32 v216, 0x3fb504f3, v213
	s_waitcnt vmcnt(3)
	v_sub_f32_e32 v129, v129, v212
	v_sub_f32_e32 v128, v128, v212
	v_sub_f32_e32 v131, v131, v212
	v_sub_f32_e32 v130, v130, v212
	v_pk_mul_f32 v[130:131], v[130:131], v[216:217] op_sel_hi:[1,0]
	v_pk_mul_f32 v[128:129], v[128:129], v[216:217] op_sel_hi:[1,0]
	v_pk_fma_f32 v[130:131], v[86:87], v[130:131], v[190:191]
	v_pk_fma_f32 v[128:129], v[84:85], v[128:129], v[192:193]
	v_pk_fma_f32 v[126:127], v[126:127], v[178:179], v[130:131]
	v_pk_fma_f32 v[124:125], v[124:125], v[180:181], v[128:129]
	global_store_dwordx4 v[214:215], v[124:127], off
	s_waitcnt vmcnt(3)
	s_nop 0
	v_sub_f32_e32 v125, v133, v212
	v_sub_f32_e32 v124, v132, v212
	v_sub_f32_e32 v127, v135, v212
	v_sub_f32_e32 v126, v134, v212
	v_pk_mul_f32 v[126:127], v[126:127], v[216:217] op_sel_hi:[1,0]
	v_pk_mul_f32 v[124:125], v[124:125], v[216:217] op_sel_hi:[1,0]
	v_pk_fma_f32 v[126:127], v[74:75], v[126:127], v[186:187]
	v_pk_fma_f32 v[124:125], v[72:73], v[124:125], v[188:189]
	v_pk_fma_f32 v[122:123], v[122:123], v[174:175], v[126:127]
	v_pk_fma_f32 v[120:121], v[120:121], v[176:177], v[124:125]
	global_store_dwordx4 v[214:215], v[120:123], off offset:64
	s_waitcnt vmcnt(3)
	s_nop 0
	v_sub_f32_e32 v121, v137, v212
	v_sub_f32_e32 v120, v136, v212
	v_sub_f32_e32 v123, v139, v212
	v_sub_f32_e32 v122, v138, v212
	v_pk_mul_f32 v[122:123], v[216:217], v[122:123] op_sel_hi:[0,1]
	v_pk_mul_f32 v[120:121], v[216:217], v[120:121] op_sel_hi:[0,1]
	v_pk_fma_f32 v[120:121], v[68:69], v[120:121], v[184:185]
	v_pk_fma_f32 v[122:123], v[70:71], v[122:123], v[182:183]
	v_pk_fma_f32 v[116:117], v[116:117], v[172:173], v[120:121]
	v_pk_fma_f32 v[118:119], v[118:119], v[170:171], v[122:123]
	global_store_dwordx4 v[214:215], v[116:119], off offset:512
	s_waitcnt vmcnt(3)
	s_nop 0
	v_sub_f32_e32 v117, v141, v212
	v_sub_f32_e32 v116, v140, v212
	v_sub_f32_e32 v119, v143, v212
	v_sub_f32_e32 v118, v142, v212
	v_pk_mul_f32 v[118:119], v[216:217], v[118:119] op_sel_hi:[0,1]
	v_pk_mul_f32 v[116:117], v[216:217], v[116:117] op_sel_hi:[0,1]
	v_pk_fma_f32 v[116:117], v[64:65], v[116:117], v[168:169]
	v_pk_fma_f32 v[118:119], v[66:67], v[118:119], v[166:167]
	v_pk_fma_f32 v[112:113], v[112:113], v[164:165], v[116:117]
	v_pk_fma_f32 v[114:115], v[114:115], v[162:163], v[118:119]
	global_store_dwordx4 v[214:215], v[112:115], off offset:576
	s_and_b64 vcc, exec, s[6:7]
	s_cbranch_vccnz .Lmy_epi_w1
	s_sleep 30
.Lmy_epi_w1:
	s_nop 1
	v_add_u32_e32 v112, s17, v227
	v_ashrrev_i32_e32 v113, 31, v112
	v_lshl_add_u64 v[114:115], v[112:113], 3, s[12:13]
	global_load_dwordx2 v[128:129], v[114:115], off
	v_lshlrev_b64 v[112:113], 12, v[112:113]
	v_lshl_add_u64 v[112:113], s[0:1], 0, v[112:113]
	v_lshl_add_u64 v[130:131], v[112:113], 0, v[160:161]
	global_load_dwordx4 v[112:115], v[130:131], off
	global_load_dwordx4 v[116:119], v[130:131], off offset:64
	global_load_dwordx4 v[120:123], v[130:131], off offset:512
	global_load_dwordx4 v[124:127], v[130:131], off offset:576
	s_waitcnt vmcnt(4)
	v_mul_f32_e32 v132, 0x3fb504f3, v129
	s_waitcnt vmcnt(3)
	v_sub_f32_e32 v113, v113, v128
	v_sub_f32_e32 v112, v112, v128
	v_sub_f32_e32 v115, v115, v128
	v_sub_f32_e32 v114, v114, v128
	v_pk_mul_f32 v[114:115], v[114:115], v[132:133] op_sel_hi:[1,0]
	v_pk_mul_f32 v[112:113], v[112:113], v[132:133] op_sel_hi:[1,0]
	v_pk_fma_f32 v[114:115], v[86:87], v[114:115], v[190:191]
	v_pk_fma_f32 v[112:113], v[84:85], v[112:113], v[192:193]
	v_pk_fma_f32 v[110:111], v[110:111], v[178:179], v[114:115]
	v_pk_fma_f32 v[108:109], v[108:109], v[180:181], v[112:113]
	global_store_dwordx4 v[130:131], v[108:111], off
	s_waitcnt vmcnt(3)
	s_nop 0
	v_sub_f32_e32 v109, v117, v128
	v_sub_f32_e32 v108, v116, v128
	v_sub_f32_e32 v111, v119, v128
	v_sub_f32_e32 v110, v118, v128
	v_pk_mul_f32 v[110:111], v[110:111], v[132:133] op_sel_hi:[1,0]
	v_pk_mul_f32 v[108:109], v[108:109], v[132:133] op_sel_hi:[1,0]
	v_pk_fma_f32 v[110:111], v[74:75], v[110:111], v[186:187]
	v_pk_fma_f32 v[108:109], v[72:73], v[108:109], v[188:189]
	v_pk_fma_f32 v[106:107], v[106:107], v[174:175], v[110:111]
	v_pk_fma_f32 v[104:105], v[104:105], v[176:177], v[108:109]
	global_store_dwordx4 v[130:131], v[104:107], off offset:64
	s_waitcnt vmcnt(3)
	s_nop 0
	v_sub_f32_e32 v105, v121, v128
	v_sub_f32_e32 v104, v120, v128
	v_sub_f32_e32 v107, v123, v128
	v_sub_f32_e32 v106, v122, v128
	v_pk_mul_f32 v[106:107], v[132:133], v[106:107] op_sel_hi:[0,1]
	v_pk_mul_f32 v[104:105], v[132:133], v[104:105] op_sel_hi:[0,1]
	v_pk_fma_f32 v[104:105], v[68:69], v[104:105], v[184:185]
	v_pk_fma_f32 v[106:107], v[70:71], v[106:107], v[182:183]
	v_pk_fma_f32 v[100:101], v[100:101], v[172:173], v[104:105]
	v_pk_fma_f32 v[102:103], v[102:103], v[170:171], v[106:107]
	global_store_dwordx4 v[130:131], v[100:103], off offset:512
	s_waitcnt vmcnt(3)
	s_nop 0
	v_sub_f32_e32 v101, v125, v128
	v_sub_f32_e32 v100, v124, v128
	v_sub_f32_e32 v103, v127, v128
	v_sub_f32_e32 v102, v126, v128
	v_pk_mul_f32 v[102:103], v[132:133], v[102:103] op_sel_hi:[0,1]
	v_pk_mul_f32 v[100:101], v[132:133], v[100:101] op_sel_hi:[0,1]
	v_pk_fma_f32 v[100:101], v[64:65], v[100:101], v[168:169]
	v_pk_fma_f32 v[102:103], v[66:67], v[102:103], v[166:167]
	v_pk_fma_f32 v[96:97], v[96:97], v[164:165], v[100:101]
	v_pk_fma_f32 v[98:99], v[98:99], v[162:163], v[102:103]
	global_store_dwordx4 v[130:131], v[96:99], off offset:576
	s_and_b64 vcc, exec, s[6:7]
	s_cbranch_vccnz .Lmy_epi_w2
	s_sleep 30
.Lmy_epi_w2:
	s_nop 1
	v_add_u32_e32 v96, s17, v228
	v_ashrrev_i32_e32 v97, 31, v96
	v_lshl_add_u64 v[98:99], v[96:97], 3, s[12:13]
	global_load_dwordx2 v[112:113], v[98:99], off
	v_lshlrev_b64 v[96:97], 12, v[96:97]
	v_lshl_add_u64 v[96:97], s[0:1], 0, v[96:97]
	v_lshl_add_u64 v[114:115], v[96:97], 0, v[160:161]
	global_load_dwordx4 v[96:99], v[114:115], off
	global_load_dwordx4 v[100:103], v[114:115], off offset:64
	global_load_dwordx4 v[104:107], v[114:115], off offset:512
	global_load_dwordx4 v[108:111], v[114:115], off offset:576
	s_waitcnt vmcnt(4)
	v_mul_f32_e32 v116, 0x3fb504f3, v113
	s_waitcnt vmcnt(3)
	v_sub_f32_e32 v97, v97, v112
	v_sub_f32_e32 v96, v96, v112
	v_sub_f32_e32 v99, v99, v112
	v_sub_f32_e32 v98, v98, v112
	v_pk_mul_f32 v[98:99], v[98:99], v[116:117] op_sel_hi:[1,0]
	v_pk_mul_f32 v[96:97], v[96:97], v[116:117] op_sel_hi:[1,0]
	v_pk_fma_f32 v[98:99], v[86:87], v[98:99], v[190:191]
	v_pk_fma_f32 v[96:97], v[84:85], v[96:97], v[192:193]
	v_pk_fma_f32 v[94:95], v[94:95], v[178:179], v[98:99]
	v_pk_fma_f32 v[92:93], v[92:93], v[180:181], v[96:97]
	global_store_dwordx4 v[114:115], v[92:95], off
	s_waitcnt vmcnt(3)
	s_nop 0
	v_sub_f32_e32 v93, v101, v112
	v_sub_f32_e32 v92, v100, v112
	v_sub_f32_e32 v95, v103, v112
	v_sub_f32_e32 v94, v102, v112
	v_pk_mul_f32 v[94:95], v[94:95], v[116:117] op_sel_hi:[1,0]
	v_pk_mul_f32 v[92:93], v[92:93], v[116:117] op_sel_hi:[1,0]
	v_pk_fma_f32 v[94:95], v[74:75], v[94:95], v[186:187]
	v_pk_fma_f32 v[92:93], v[72:73], v[92:93], v[188:189]
	v_pk_fma_f32 v[90:91], v[90:91], v[174:175], v[94:95]
	v_pk_fma_f32 v[88:89], v[88:89], v[176:177], v[92:93]
	global_store_dwordx4 v[114:115], v[88:91], off offset:64
	s_waitcnt vmcnt(3)
	s_nop 0
	v_sub_f32_e32 v89, v105, v112
	v_sub_f32_e32 v88, v104, v112
	v_sub_f32_e32 v91, v107, v112
	v_sub_f32_e32 v90, v106, v112
	v_pk_mul_f32 v[90:91], v[116:117], v[90:91] op_sel_hi:[0,1]
	v_pk_mul_f32 v[88:89], v[116:117], v[88:89] op_sel_hi:[0,1]
	v_pk_fma_f32 v[88:89], v[68:69], v[88:89], v[184:185]
	v_pk_fma_f32 v[90:91], v[70:71], v[90:91], v[182:183]
	v_pk_fma_f32 v[80:81], v[80:81], v[172:173], v[88:89]
	v_pk_fma_f32 v[82:83], v[82:83], v[170:171], v[90:91]
	global_store_dwordx4 v[114:115], v[80:83], off offset:512
	s_waitcnt vmcnt(3)
	s_nop 0
	v_sub_f32_e32 v81, v109, v112
	v_sub_f32_e32 v80, v108, v112
	v_sub_f32_e32 v83, v111, v112
	v_sub_f32_e32 v82, v110, v112
	v_pk_mul_f32 v[82:83], v[116:117], v[82:83] op_sel_hi:[0,1]
	v_pk_mul_f32 v[80:81], v[116:117], v[80:81] op_sel_hi:[0,1]
	v_pk_fma_f32 v[80:81], v[64:65], v[80:81], v[168:169]
	v_pk_fma_f32 v[82:83], v[66:67], v[82:83], v[166:167]
	v_pk_fma_f32 v[76:77], v[76:77], v[164:165], v[80:81]
	v_pk_fma_f32 v[78:79], v[78:79], v[162:163], v[82:83]
	global_store_dwordx4 v[114:115], v[76:79], off offset:576
	s_and_b64 vcc, exec, s[6:7]
	s_cbranch_vccnz .Lmy_epi_w3
	s_sleep 30
.Lmy_epi_w3:
	s_nop 1
	v_add_u32_e32 v76, 0x80, v194
	v_ashrrev_i32_e32 v77, 31, v76
	v_lshl_add_u64 v[78:79], v[76:77], 3, s[12:13]
	global_load_dwordx2 v[96:97], v[78:79], off
	v_lshlrev_b64 v[76:77], 12, v[76:77]
	v_lshl_add_u64 v[76:77], s[0:1], 0, v[76:77]
	v_lshl_add_u64 v[98:99], v[76:77], 0, v[160:161]
	global_load_dwordx4 v[76:79], v[98:99], off
	global_load_dwordx4 v[80:83], v[98:99], off offset:64
	global_load_dwordx4 v[88:91], v[98:99], off offset:512
	global_load_dwordx4 v[92:95], v[98:99], off offset:576
	s_waitcnt vmcnt(4)
	v_mul_f32_e32 v100, 0x3fb504f3, v97
	s_waitcnt vmcnt(3)
	v_sub_f32_e32 v77, v77, v96
	v_sub_f32_e32 v76, v76, v96
	v_sub_f32_e32 v79, v79, v96
	v_sub_f32_e32 v78, v78, v96
	v_pk_mul_f32 v[78:79], v[78:79], v[100:101] op_sel_hi:[1,0]
	v_pk_mul_f32 v[76:77], v[76:77], v[100:101] op_sel_hi:[1,0]
	v_pk_fma_f32 v[78:79], v[86:87], v[78:79], v[190:191]
	v_pk_fma_f32 v[76:77], v[84:85], v[76:77], v[192:193]
	v_pk_fma_f32 v[62:63], v[62:63], v[178:179], v[78:79]
	v_pk_fma_f32 v[60:61], v[60:61], v[180:181], v[76:77]
	global_store_dwordx4 v[98:99], v[60:63], off
	s_waitcnt vmcnt(3)
	s_nop 0
	v_sub_f32_e32 v61, v81, v96
	v_sub_f32_e32 v60, v80, v96
	v_sub_f32_e32 v63, v83, v96
	v_sub_f32_e32 v62, v82, v96
	v_pk_mul_f32 v[62:63], v[62:63], v[100:101] op_sel_hi:[1,0]
	v_pk_mul_f32 v[60:61], v[60:61], v[100:101] op_sel_hi:[1,0]
	v_pk_fma_f32 v[62:63], v[74:75], v[62:63], v[186:187]
	v_pk_fma_f32 v[60:61], v[72:73], v[60:61], v[188:189]
	v_pk_fma_f32 v[58:59], v[58:59], v[174:175], v[62:63]
	v_pk_fma_f32 v[56:57], v[56:57], v[176:177], v[60:61]
	global_store_dwordx4 v[98:99], v[56:59], off offset:64
	s_waitcnt vmcnt(3)
	s_nop 0
	v_sub_f32_e32 v57, v89, v96
	v_sub_f32_e32 v56, v88, v96
	v_sub_f32_e32 v59, v91, v96
	v_sub_f32_e32 v58, v90, v96
	v_pk_mul_f32 v[58:59], v[100:101], v[58:59] op_sel_hi:[0,1]
	v_pk_mul_f32 v[56:57], v[100:101], v[56:57] op_sel_hi:[0,1]
	v_pk_fma_f32 v[56:57], v[68:69], v[56:57], v[184:185]
	v_pk_fma_f32 v[58:59], v[70:71], v[58:59], v[182:183]
	v_pk_fma_f32 v[52:53], v[52:53], v[172:173], v[56:57]
	v_pk_fma_f32 v[54:55], v[54:55], v[170:171], v[58:59]
	global_store_dwordx4 v[98:99], v[52:55], off offset:512
	s_waitcnt vmcnt(3)
	s_nop 0
	v_sub_f32_e32 v53, v93, v96
	v_sub_f32_e32 v52, v92, v96
	v_sub_f32_e32 v55, v95, v96
	v_sub_f32_e32 v54, v94, v96
	v_pk_mul_f32 v[54:55], v[100:101], v[54:55] op_sel_hi:[0,1]
	v_pk_mul_f32 v[52:53], v[100:101], v[52:53] op_sel_hi:[0,1]
	v_pk_fma_f32 v[52:53], v[64:65], v[52:53], v[168:169]
	v_pk_fma_f32 v[54:55], v[66:67], v[54:55], v[166:167]
	v_pk_fma_f32 v[48:49], v[48:49], v[164:165], v[52:53]
	v_pk_fma_f32 v[50:51], v[50:51], v[162:163], v[54:55]
	global_store_dwordx4 v[98:99], v[48:51], off offset:576
	s_and_b64 vcc, exec, s[6:7]
	s_cbranch_vccnz .Lmy_epi_w4
	s_sleep 30
.Lmy_epi_w4:
	s_nop 1
	v_add_u32_e32 v48, 0x90, v194
	v_ashrrev_i32_e32 v49, 31, v48
	v_lshl_add_u64 v[50:51], v[48:49], 3, s[12:13]
	global_load_dwordx2 v[76:77], v[50:51], off
	v_lshlrev_b64 v[48:49], 12, v[48:49]
	v_lshl_add_u64 v[48:49], s[0:1], 0, v[48:49]
	v_lshl_add_u64 v[78:79], v[48:49], 0, v[160:161]
	global_load_dwordx4 v[48:51], v[78:79], off
	global_load_dwordx4 v[52:55], v[78:79], off offset:64
	global_load_dwordx4 v[56:59], v[78:79], off offset:512
	global_load_dwordx4 v[60:63], v[78:79], off offset:576
	s_waitcnt vmcnt(4)
	v_mul_f32_e32 v80, 0x3fb504f3, v77
	s_waitcnt vmcnt(3)
	v_sub_f32_e32 v49, v49, v76
	v_sub_f32_e32 v48, v48, v76
	v_sub_f32_e32 v51, v51, v76
	v_sub_f32_e32 v50, v50, v76
	v_pk_mul_f32 v[50:51], v[50:51], v[80:81] op_sel_hi:[1,0]
	v_pk_mul_f32 v[48:49], v[48:49], v[80:81] op_sel_hi:[1,0]
	v_pk_fma_f32 v[50:51], v[86:87], v[50:51], v[190:191]
	v_pk_fma_f32 v[48:49], v[84:85], v[48:49], v[192:193]
	v_pk_fma_f32 v[46:47], v[46:47], v[178:179], v[50:51]
	v_pk_fma_f32 v[44:45], v[44:45], v[180:181], v[48:49]
	global_store_dwordx4 v[78:79], v[44:47], off
	s_waitcnt vmcnt(3)
	s_nop 0
	v_sub_f32_e32 v45, v53, v76
	v_sub_f32_e32 v44, v52, v76
	v_sub_f32_e32 v47, v55, v76
	v_sub_f32_e32 v46, v54, v76
	v_pk_mul_f32 v[46:47], v[46:47], v[80:81] op_sel_hi:[1,0]
	v_pk_mul_f32 v[44:45], v[44:45], v[80:81] op_sel_hi:[1,0]
	v_pk_fma_f32 v[46:47], v[74:75], v[46:47], v[186:187]
	v_pk_fma_f32 v[44:45], v[72:73], v[44:45], v[188:189]
	v_pk_fma_f32 v[42:43], v[42:43], v[174:175], v[46:47]
	v_pk_fma_f32 v[40:41], v[40:41], v[176:177], v[44:45]
	global_store_dwordx4 v[78:79], v[40:43], off offset:64
	s_waitcnt vmcnt(3)
	s_nop 0
	v_sub_f32_e32 v41, v57, v76
	v_sub_f32_e32 v40, v56, v76
	v_sub_f32_e32 v43, v59, v76
	v_sub_f32_e32 v42, v58, v76
	v_pk_mul_f32 v[42:43], v[80:81], v[42:43] op_sel_hi:[0,1]
	v_pk_mul_f32 v[40:41], v[80:81], v[40:41] op_sel_hi:[0,1]
	v_pk_fma_f32 v[40:41], v[68:69], v[40:41], v[184:185]
	v_pk_fma_f32 v[42:43], v[70:71], v[42:43], v[182:183]
	v_pk_fma_f32 v[36:37], v[36:37], v[172:173], v[40:41]
	v_pk_fma_f32 v[38:39], v[38:39], v[170:171], v[42:43]
	global_store_dwordx4 v[78:79], v[36:39], off offset:512
	s_waitcnt vmcnt(3)
	s_nop 0
	v_sub_f32_e32 v37, v61, v76
	v_sub_f32_e32 v36, v60, v76
	v_sub_f32_e32 v39, v63, v76
	v_sub_f32_e32 v38, v62, v76
	v_pk_mul_f32 v[38:39], v[80:81], v[38:39] op_sel_hi:[0,1]
	v_pk_mul_f32 v[36:37], v[80:81], v[36:37] op_sel_hi:[0,1]
	v_pk_fma_f32 v[36:37], v[64:65], v[36:37], v[168:169]
	v_pk_fma_f32 v[38:39], v[66:67], v[38:39], v[166:167]
	v_pk_fma_f32 v[32:33], v[32:33], v[164:165], v[36:37]
	v_pk_fma_f32 v[34:35], v[34:35], v[162:163], v[38:39]
	global_store_dwordx4 v[78:79], v[32:35], off offset:576
	s_and_b64 vcc, exec, s[6:7]
	s_cbranch_vccnz .Lmy_epi_w5
	s_sleep 30
.Lmy_epi_w5:
	s_nop 1
	v_add_u32_e32 v32, 0xa0, v194
	v_ashrrev_i32_e32 v33, 31, v32
	v_lshl_add_u64 v[34:35], v[32:33], 3, s[12:13]
	global_load_dwordx2 v[48:49], v[34:35], off
	v_lshlrev_b64 v[32:33], 12, v[32:33]
	v_lshl_add_u64 v[32:33], s[0:1], 0, v[32:33]
	v_lshl_add_u64 v[50:51], v[32:33], 0, v[160:161]
	global_load_dwordx4 v[32:35], v[50:51], off
	global_load_dwordx4 v[36:39], v[50:51], off offset:64
	global_load_dwordx4 v[40:43], v[50:51], off offset:512
	global_load_dwordx4 v[44:47], v[50:51], off offset:576
	s_waitcnt vmcnt(4)
	v_mul_f32_e32 v52, 0x3fb504f3, v49
	s_waitcnt vmcnt(3)
	v_sub_f32_e32 v33, v33, v48
	v_sub_f32_e32 v32, v32, v48
	v_sub_f32_e32 v35, v35, v48
	v_sub_f32_e32 v34, v34, v48
	v_pk_mul_f32 v[34:35], v[34:35], v[52:53] op_sel_hi:[1,0]
	v_pk_mul_f32 v[32:33], v[32:33], v[52:53] op_sel_hi:[1,0]
	v_pk_fma_f32 v[34:35], v[86:87], v[34:35], v[190:191]
	v_pk_fma_f32 v[32:33], v[84:85], v[32:33], v[192:193]
	v_pk_fma_f32 v[30:31], v[30:31], v[178:179], v[34:35]
	v_pk_fma_f32 v[28:29], v[28:29], v[180:181], v[32:33]
	global_store_dwordx4 v[50:51], v[28:31], off
	s_waitcnt vmcnt(3)
	s_nop 0
	v_sub_f32_e32 v29, v37, v48
	v_sub_f32_e32 v28, v36, v48
	v_sub_f32_e32 v31, v39, v48
	v_sub_f32_e32 v30, v38, v48
	v_pk_mul_f32 v[30:31], v[30:31], v[52:53] op_sel_hi:[1,0]
	v_pk_mul_f32 v[28:29], v[28:29], v[52:53] op_sel_hi:[1,0]
	v_pk_fma_f32 v[30:31], v[74:75], v[30:31], v[186:187]
	v_pk_fma_f32 v[28:29], v[72:73], v[28:29], v[188:189]
	v_pk_fma_f32 v[26:27], v[26:27], v[174:175], v[30:31]
	v_pk_fma_f32 v[24:25], v[24:25], v[176:177], v[28:29]
	global_store_dwordx4 v[50:51], v[24:27], off offset:64
	s_waitcnt vmcnt(3)
	s_nop 0
	v_sub_f32_e32 v25, v41, v48
	v_sub_f32_e32 v24, v40, v48
	v_sub_f32_e32 v27, v43, v48
	v_sub_f32_e32 v26, v42, v48
	v_pk_mul_f32 v[26:27], v[52:53], v[26:27] op_sel_hi:[0,1]
	v_pk_mul_f32 v[24:25], v[52:53], v[24:25] op_sel_hi:[0,1]
	v_pk_fma_f32 v[24:25], v[68:69], v[24:25], v[184:185]
	v_pk_fma_f32 v[26:27], v[70:71], v[26:27], v[182:183]
	v_pk_fma_f32 v[20:21], v[20:21], v[172:173], v[24:25]
	v_pk_fma_f32 v[22:23], v[22:23], v[170:171], v[26:27]
	global_store_dwordx4 v[50:51], v[20:23], off offset:512
	s_waitcnt vmcnt(3)
	s_nop 0
	v_sub_f32_e32 v21, v45, v48
	v_sub_f32_e32 v20, v44, v48
	v_sub_f32_e32 v23, v47, v48
	v_sub_f32_e32 v22, v46, v48
	v_pk_mul_f32 v[22:23], v[52:53], v[22:23] op_sel_hi:[0,1]
	v_pk_mul_f32 v[20:21], v[52:53], v[20:21] op_sel_hi:[0,1]
	v_pk_fma_f32 v[20:21], v[64:65], v[20:21], v[168:169]
	v_pk_fma_f32 v[22:23], v[66:67], v[22:23], v[166:167]
	v_pk_fma_f32 v[16:17], v[16:17], v[164:165], v[20:21]
	v_pk_fma_f32 v[18:19], v[18:19], v[162:163], v[22:23]
	global_store_dwordx4 v[50:51], v[16:19], off offset:576
	s_and_b64 vcc, exec, s[6:7]
	s_cbranch_vccnz .Lmy_epi_w6
	s_sleep 30
.Lmy_epi_w6:
	s_nop 1
	v_add_u32_e32 v16, 0xb0, v194
	v_ashrrev_i32_e32 v17, 31, v16
	v_lshl_add_u64 v[18:19], v[16:17], 3, s[12:13]
	global_load_dwordx2 v[18:19], v[18:19], off
	v_lshlrev_b64 v[16:17], 12, v[16:17]
	v_lshl_add_u64 v[16:17], s[0:1], 0, v[16:17]
	v_lshl_add_u64 v[16:17], v[16:17], 0, v[160:161]
	global_load_dwordx4 v[20:23], v[16:17], off
	global_load_dwordx4 v[24:27], v[16:17], off offset:64
	global_load_dwordx4 v[28:31], v[16:17], off offset:512
	global_load_dwordx4 v[32:35], v[16:17], off offset:576
	s_waitcnt vmcnt(4)
	v_mul_f32_e32 v36, 0x3fb504f3, v19
	s_waitcnt vmcnt(3)
	v_sub_f32_e32 v21, v21, v18
	v_sub_f32_e32 v20, v20, v18
	v_sub_f32_e32 v23, v23, v18
	v_sub_f32_e32 v22, v22, v18
	v_pk_mul_f32 v[22:23], v[22:23], v[36:37] op_sel_hi:[1,0]
	v_pk_mul_f32 v[20:21], v[20:21], v[36:37] op_sel_hi:[1,0]
	v_pk_fma_f32 v[22:23], v[86:87], v[22:23], v[190:191]
	v_pk_fma_f32 v[20:21], v[84:85], v[20:21], v[192:193]
	v_pk_fma_f32 v[14:15], v[14:15], v[178:179], v[22:23]
	v_pk_fma_f32 v[12:13], v[12:13], v[180:181], v[20:21]
	global_store_dwordx4 v[16:17], v[12:15], off
	s_waitcnt vmcnt(3)
	s_nop 0
	v_sub_f32_e32 v13, v25, v18
	v_sub_f32_e32 v12, v24, v18
	v_sub_f32_e32 v15, v27, v18
	v_sub_f32_e32 v14, v26, v18
	v_pk_mul_f32 v[14:15], v[14:15], v[36:37] op_sel_hi:[1,0]
	v_pk_mul_f32 v[12:13], v[12:13], v[36:37] op_sel_hi:[1,0]
	v_pk_fma_f32 v[14:15], v[74:75], v[14:15], v[186:187]
	v_pk_fma_f32 v[12:13], v[72:73], v[12:13], v[188:189]
	v_pk_fma_f32 v[10:11], v[10:11], v[174:175], v[14:15]
	v_pk_fma_f32 v[8:9], v[8:9], v[176:177], v[12:13]
	global_store_dwordx4 v[16:17], v[8:11], off offset:64
	s_waitcnt vmcnt(3)
	s_nop 0
	v_sub_f32_e32 v9, v29, v18
	v_sub_f32_e32 v8, v28, v18
	v_sub_f32_e32 v11, v31, v18
	v_sub_f32_e32 v10, v30, v18
	v_pk_mul_f32 v[10:11], v[36:37], v[10:11] op_sel_hi:[0,1]
	v_pk_mul_f32 v[8:9], v[36:37], v[8:9] op_sel_hi:[0,1]
	v_pk_fma_f32 v[8:9], v[68:69], v[8:9], v[184:185]
	v_pk_fma_f32 v[10:11], v[70:71], v[10:11], v[182:183]
	v_pk_fma_f32 v[4:5], v[4:5], v[172:173], v[8:9]
	v_pk_fma_f32 v[6:7], v[6:7], v[170:171], v[10:11]
	global_store_dwordx4 v[16:17], v[4:7], off offset:512
	s_waitcnt vmcnt(3)
	s_nop 0
	v_sub_f32_e32 v5, v33, v18
	v_sub_f32_e32 v4, v32, v18
	v_sub_f32_e32 v7, v35, v18
	v_sub_f32_e32 v6, v34, v18
	v_pk_mul_f32 v[6:7], v[36:37], v[6:7] op_sel_hi:[0,1]
	v_pk_mul_f32 v[4:5], v[36:37], v[4:5] op_sel_hi:[0,1]
	v_pk_fma_f32 v[4:5], v[64:65], v[4:5], v[168:169]
	v_pk_fma_f32 v[6:7], v[66:67], v[6:7], v[166:167]
	v_pk_fma_f32 v[0:1], v[0:1], v[164:165], v[4:5]
	v_pk_fma_f32 v[2:3], v[2:3], v[162:163], v[6:7]
	global_store_dwordx4 v[16:17], v[0:3], off offset:576
	s_and_b64 vcc, exec, s[6:7]
	s_mov_b64 s[6:7], -1
	s_cbranch_vccnz .LBB0_1150

.LBB0_1378:
	s_ashr_i32 s25, s76, 3
	s_mul_hi_i32 s35, s25, 0x9000
	s_mul_i32 s25, s25, 0x9000
	s_add_u32 s34, s12, s25
	s_addc_u32 s35, s13, s35
	s_lshl_b32 s25, s76, 8
	v_add_u32_e32 v194, s25, v151
	v_lshl_add_u64 v[128:129], s[20:21], 0, v[160:161]
	v_ashrrev_i32_e32 v195, 31, v194
	global_load_dwordx4 v[162:165], v[128:129], off
	v_lshl_add_u64 v[130:131], s[34:35], 0, v[160:161]
	global_load_dwordx4 v[170:173], v[128:129], off offset:64
	global_load_dwordx4 v[174:177], v[128:129], off offset:512
	global_load_dwordx4 v[178:181], v[130:131], off
	global_load_dwordx4 v[182:185], v[130:131], off offset:64
	global_load_dwordx4 v[232:235], v[128:129], off offset:576
	global_load_dwordx4 v[236:239], v[130:131], off offset:512
	global_load_dwordx4 v[240:243], v[130:131], off offset:576
	v_lshl_add_u64 v[128:129], v[194:195], 3, s[14:15]
	v_lshlrev_b64 v[166:167], 12, v[194:195]
	global_load_dwordx2 v[206:207], v[128:129], off
	v_lshl_add_u64 v[128:129], s[16:17], 0, v[166:167]
	v_lshl_add_u64 v[128:129], v[128:129], 0, v[160:161]
	global_load_dwordx4 v[244:247], v[128:129], off
	global_load_dwordx4 v[248:251], v[128:129], off offset:64
	global_load_dwordx4 v[216:219], v[128:129], off offset:512
	global_load_dwordx4 v[212:215], v[128:129], off offset:576
	v_lshl_add_u64 v[128:129], s[18:19], 0, v[160:161]
	global_load_dwordx4 v[140:143], v[128:129], off
	global_load_dwordx4 v[136:139], v[128:129], off offset:64
	global_load_dwordx4 v[132:135], v[128:129], off offset:512
	s_nop 0
	global_load_dwordx4 v[128:131], v[128:129], off offset:576
	v_lshl_add_u64 v[166:167], s[8:9], 0, v[166:167]
	v_lshl_add_u64 v[198:199], v[166:167], 0, v[160:161]
	s_waitcnt vmcnt(0)
	v_pk_mul_f32 v[168:169], v[172:173], s[58:59] op_sel_hi:[1,0]
	v_pk_mul_f32 v[188:189], v[170:171], s[58:59] op_sel_hi:[1,0]
	v_pk_mul_f32 v[170:171], v[176:177], s[58:59] op_sel_hi:[1,0]
	v_pk_fma_f32 v[176:177], v[178:179], 0.5, 0.5 op_sel_hi:[1,0,0]
	v_pk_mul_f32 v[172:173], v[234:235], s[58:59] op_sel_hi:[1,0]
	v_pk_mul_f32 v[192:193], v[232:233], s[58:59] op_sel_hi:[1,0]
	v_pk_fma_f32 v[178:179], v[184:185], 0.5, 0.5 op_sel_hi:[1,0,0]
	v_pk_fma_f32 v[184:185], v[236:237], 0.5, 0.5 op_sel_hi:[1,0,0]
	v_pk_mul_f32 v[166:167], v[164:165], s[58:59] op_sel_hi:[1,0]
	v_mul_f32_e32 v232, 0x3fb504f3, v207
	v_sub_f32_e32 v235, v245, v206
	v_sub_f32_e32 v234, v244, v206
	v_sub_f32_e32 v237, v247, v206
	v_sub_f32_e32 v236, v246, v206
	v_sub_f32_e32 v213, v213, v206
	v_sub_f32_e32 v212, v212, v206
	v_pk_mul_f32 v[186:187], v[162:163], s[58:59] op_sel_hi:[1,0]
	v_pk_mul_f32 v[190:191], v[174:175], s[58:59] op_sel_hi:[1,0]
	v_pk_fma_f32 v[174:175], v[180:181], 0.5, 0.5 op_sel_hi:[1,0,0]
	v_pk_fma_f32 v[180:181], v[182:183], 0.5, 0.5 op_sel_hi:[1,0,0]
	v_pk_fma_f32 v[182:183], v[238:239], 0.5, 0.5 op_sel_hi:[1,0,0]
	v_pk_fma_f32 v[164:165], v[240:241], 0.5, 0.5 op_sel_hi:[1,0,0]
	v_sub_f32_e32 v239, v249, v206
	v_sub_f32_e32 v238, v248, v206
	v_sub_f32_e32 v241, v251, v206
	v_sub_f32_e32 v240, v250, v206
	v_sub_f32_e32 v217, v217, v206
	v_sub_f32_e32 v216, v216, v206
	v_sub_f32_e32 v219, v219, v206
	v_sub_f32_e32 v218, v218, v206
	v_sub_f32_e32 v207, v215, v206
	v_sub_f32_e32 v206, v214, v206
	v_pk_mul_f32 v[214:215], v[236:237], v[232:233] op_sel_hi:[1,0]
	v_pk_mul_f32 v[234:235], v[234:235], v[232:233] op_sel_hi:[1,0]
	v_pk_mul_f32 v[212:213], v[232:233], v[212:213] op_sel_hi:[0,1]
	v_pk_mul_f32 v[236:237], v[240:241], v[232:233] op_sel_hi:[1,0]
	v_pk_mul_f32 v[238:239], v[238:239], v[232:233] op_sel_hi:[1,0]
	v_pk_mul_f32 v[218:219], v[232:233], v[218:219] op_sel_hi:[0,1]
	v_pk_mul_f32 v[216:217], v[232:233], v[216:217] op_sel_hi:[0,1]
	v_pk_mul_f32 v[206:207], v[232:233], v[206:207] op_sel_hi:[0,1]
	v_pk_fma_f32 v[232:233], v[140:141], v[234:235], v[186:187]
	v_pk_fma_f32 v[214:215], v[142:143], v[214:215], v[166:167]
	v_pk_fma_f32 v[212:213], v[128:129], v[212:213], v[192:193]
	v_pk_fma_f32 v[162:163], v[242:243], 0.5, 0.5 op_sel_hi:[1,0,0]
	v_pk_fma_f32 v[234:235], v[136:137], v[238:239], v[188:189]
	v_pk_fma_f32 v[236:237], v[138:139], v[236:237], v[168:169]
	v_pk_fma_f32 v[216:217], v[132:133], v[216:217], v[190:191]
	v_pk_fma_f32 v[218:219], v[134:135], v[218:219], v[170:171]
	v_pk_fma_f32 v[206:207], v[130:131], v[206:207], v[172:173]
	v_pk_fma_f32 v[126:127], v[126:127], v[174:175], v[214:215]
	v_pk_fma_f32 v[124:125], v[124:125], v[176:177], v[232:233]
	v_pk_fma_f32 v[112:113], v[112:113], v[164:165], v[212:213]
	v_pk_fma_f32 v[122:123], v[122:123], v[178:179], v[236:237]
	v_pk_fma_f32 v[120:121], v[120:121], v[180:181], v[234:235]
	v_pk_fma_f32 v[118:119], v[118:119], v[182:183], v[218:219]
	v_pk_fma_f32 v[116:117], v[116:117], v[184:185], v[216:217]
	v_pk_fma_f32 v[114:115], v[114:115], v[162:163], v[206:207]
	global_store_dwordx4 v[198:199], v[124:127], off
	global_store_dwordx4 v[198:199], v[120:123], off offset:64
	global_store_dwordx4 v[198:199], v[116:119], off offset:512
	global_store_dwordx4 v[198:199], v[112:115], off offset:576
	s_and_b64 vcc, exec, s[6:7]
	s_cbranch_vccnz .Lmy_epi_f0
	s_sleep 30
.Lmy_epi_f0:
	v_add_u32_e32 v212, s25, v227
	v_ashrrev_i32_e32 v213, 31, v212
	v_add_u32_e32 v112, s25, v226
	v_ashrrev_i32_e32 v113, 31, v112
	v_lshlrev_b64 v[206:207], 12, v[112:113]
	v_lshl_add_u64 v[114:115], v[112:113], 3, s[14:15]
	v_lshl_add_u64 v[112:113], s[16:17], 0, v[206:207]
	global_load_dwordx2 v[198:199], v[114:115], off
	v_lshl_add_u64 v[124:125], v[112:113], 0, v[160:161]
	global_load_dwordx4 v[112:115], v[124:125], off
	global_load_dwordx4 v[116:119], v[124:125], off offset:64
	global_load_dwordx4 v[120:123], v[124:125], off offset:512
	s_nop 0
	global_load_dwordx4 v[124:127], v[124:125], off offset:576
	v_lshl_add_u64 v[206:207], s[8:9], 0, v[206:207]
	v_lshl_add_u64 v[206:207], v[206:207], 0, v[160:161]
	v_lshl_add_u64 v[214:215], v[212:213], 3, s[14:15]
	v_lshlrev_b64 v[212:213], 12, v[212:213]
	v_lshl_add_u64 v[216:217], s[16:17], 0, v[212:213]
	v_lshl_add_u64 v[216:217], v[216:217], 0, v[160:161]
	s_waitcnt vmcnt(4)
	v_mul_f32_e32 v218, 0x3fb504f3, v199
	s_waitcnt vmcnt(3)
	v_sub_f32_e32 v113, v113, v198
	v_sub_f32_e32 v112, v112, v198
	v_sub_f32_e32 v115, v115, v198
	v_sub_f32_e32 v114, v114, v198
	s_waitcnt vmcnt(2)
	v_sub_f32_e32 v117, v117, v198
	v_sub_f32_e32 v116, v116, v198
	v_sub_f32_e32 v119, v119, v198
	v_sub_f32_e32 v118, v118, v198
	s_waitcnt vmcnt(1)
	v_sub_f32_e32 v121, v121, v198
	v_sub_f32_e32 v120, v120, v198
	v_sub_f32_e32 v123, v123, v198
	v_sub_f32_e32 v122, v122, v198
	s_waitcnt vmcnt(0)
	v_sub_f32_e32 v125, v125, v198
	v_sub_f32_e32 v124, v124, v198
	v_sub_f32_e32 v127, v127, v198
	v_sub_f32_e32 v126, v126, v198
	v_pk_mul_f32 v[114:115], v[114:115], v[218:219] op_sel_hi:[1,0]
	v_pk_mul_f32 v[112:113], v[112:113], v[218:219] op_sel_hi:[1,0]
	v_pk_mul_f32 v[118:119], v[118:119], v[218:219] op_sel_hi:[1,0]
	v_pk_mul_f32 v[116:117], v[116:117], v[218:219] op_sel_hi:[1,0]
	v_pk_mul_f32 v[122:123], v[218:219], v[122:123] op_sel_hi:[0,1]
	v_pk_mul_f32 v[120:121], v[218:219], v[120:121] op_sel_hi:[0,1]
	v_pk_mul_f32 v[126:127], v[218:219], v[126:127] op_sel_hi:[0,1]
	v_pk_mul_f32 v[124:125], v[218:219], v[124:125] op_sel_hi:[0,1]
	v_pk_fma_f32 v[112:113], v[140:141], v[112:113], v[186:187]
	v_pk_fma_f32 v[114:115], v[142:143], v[114:115], v[166:167]
	v_pk_fma_f32 v[116:117], v[136:137], v[116:117], v[188:189]
	v_pk_fma_f32 v[118:119], v[138:139], v[118:119], v[168:169]
	v_pk_fma_f32 v[120:121], v[132:133], v[120:121], v[190:191]
	v_pk_fma_f32 v[122:123], v[134:135], v[122:123], v[170:171]
	v_pk_fma_f32 v[124:125], v[128:129], v[124:125], v[192:193]
	v_pk_fma_f32 v[126:127], v[130:131], v[126:127], v[172:173]
	v_pk_fma_f32 v[110:111], v[110:111], v[174:175], v[114:115]
	v_pk_fma_f32 v[108:109], v[108:109], v[176:177], v[112:113]
	v_pk_fma_f32 v[106:107], v[106:107], v[178:179], v[118:119]
	v_pk_fma_f32 v[104:105], v[104:105], v[180:181], v[116:117]
	v_pk_fma_f32 v[102:103], v[102:103], v[182:183], v[122:123]
	v_pk_fma_f32 v[100:101], v[100:101], v[184:185], v[120:121]
	v_pk_fma_f32 v[98:99], v[98:99], v[162:163], v[126:127]
	v_pk_fma_f32 v[96:97], v[96:97], v[164:165], v[124:125]
	global_store_dwordx4 v[206:207], v[108:111], off
	global_store_dwordx4 v[206:207], v[104:107], off offset:64
	global_store_dwordx4 v[206:207], v[100:103], off offset:512
	global_store_dwordx4 v[206:207], v[96:99], off offset:576
	s_and_b64 vcc, exec, s[6:7]
	s_cbranch_vccnz .Lmy_epi_f1
	s_sleep 30
.Lmy_epi_f1:
	global_load_dwordx2 v[112:113], v[214:215], off
	global_load_dwordx4 v[96:99], v[216:217], off
	global_load_dwordx4 v[100:103], v[216:217], off offset:64
	global_load_dwordx4 v[104:107], v[216:217], off offset:512
	global_load_dwordx4 v[108:111], v[216:217], off offset:576
	v_add_u32_e32 v114, s25, v228
	v_lshl_add_u64 v[118:119], s[8:9], 0, v[212:213]
	v_ashrrev_i32_e32 v115, 31, v114
	v_lshl_add_u64 v[118:119], v[118:119], 0, v[160:161]
	v_lshl_add_u64 v[116:117], v[114:115], 3, s[14:15]
	v_lshlrev_b64 v[114:115], 12, v[114:115]
	v_lshl_add_u64 v[120:121], s[16:17], 0, v[114:115]
	v_lshl_add_u64 v[120:121], v[120:121], 0, v[160:161]
	s_waitcnt vmcnt(4)
	v_mul_f32_e32 v122, 0x3fb504f3, v113
	s_waitcnt vmcnt(3)
	v_sub_f32_e32 v97, v97, v112
	v_sub_f32_e32 v96, v96, v112
	v_sub_f32_e32 v99, v99, v112
	v_sub_f32_e32 v98, v98, v112
	s_waitcnt vmcnt(2)
	v_sub_f32_e32 v101, v101, v112
	v_sub_f32_e32 v100, v100, v112
	v_sub_f32_e32 v103, v103, v112
	v_sub_f32_e32 v102, v102, v112
	s_waitcnt vmcnt(1)
	v_sub_f32_e32 v105, v105, v112
	v_sub_f32_e32 v104, v104, v112
	v_sub_f32_e32 v107, v107, v112
	v_sub_f32_e32 v106, v106, v112
	s_waitcnt vmcnt(0)
	v_sub_f32_e32 v109, v109, v112
	v_sub_f32_e32 v108, v108, v112
	v_sub_f32_e32 v111, v111, v112
	v_sub_f32_e32 v110, v110, v112
	v_pk_mul_f32 v[98:99], v[98:99], v[122:123] op_sel_hi:[1,0]
	v_pk_mul_f32 v[96:97], v[96:97], v[122:123] op_sel_hi:[1,0]
	v_pk_mul_f32 v[102:103], v[102:103], v[122:123] op_sel_hi:[1,0]
	v_pk_mul_f32 v[100:101], v[100:101], v[122:123] op_sel_hi:[1,0]
	v_pk_mul_f32 v[106:107], v[122:123], v[106:107] op_sel_hi:[0,1]
	v_pk_mul_f32 v[104:105], v[122:123], v[104:105] op_sel_hi:[0,1]
	v_pk_mul_f32 v[110:111], v[122:123], v[110:111] op_sel_hi:[0,1]
	v_pk_mul_f32 v[108:109], v[122:123], v[108:109] op_sel_hi:[0,1]
	v_pk_fma_f32 v[96:97], v[140:141], v[96:97], v[186:187]
	v_pk_fma_f32 v[98:99], v[142:143], v[98:99], v[166:167]
	v_pk_fma_f32 v[100:101], v[136:137], v[100:101], v[188:189]
	v_pk_fma_f32 v[102:103], v[138:139], v[102:103], v[168:169]
	v_pk_fma_f32 v[104:105], v[132:133], v[104:105], v[190:191]
	v_pk_fma_f32 v[106:107], v[134:135], v[106:107], v[170:171]
	v_pk_fma_f32 v[108:109], v[128:129], v[108:109], v[192:193]
	v_pk_fma_f32 v[110:111], v[130:131], v[110:111], v[172:173]
	v_pk_fma_f32 v[94:95], v[94:95], v[174:175], v[98:99]
	v_pk_fma_f32 v[92:93], v[92:93], v[176:177], v[96:97]
	v_pk_fma_f32 v[90:91], v[90:91], v[178:179], v[102:103]
	v_pk_fma_f32 v[88:89], v[88:89], v[180:181], v[100:101]
	v_pk_fma_f32 v[86:87], v[86:87], v[182:183], v[106:107]
	v_pk_fma_f32 v[84:85], v[84:85], v[184:185], v[104:105]
	v_pk_fma_f32 v[82:83], v[82:83], v[162:163], v[110:111]
	v_pk_fma_f32 v[80:81], v[80:81], v[164:165], v[108:109]
	global_store_dwordx4 v[118:119], v[92:95], off
	global_store_dwordx4 v[118:119], v[88:91], off offset:64
	global_store_dwordx4 v[118:119], v[84:87], off offset:512
	global_store_dwordx4 v[118:119], v[80:83], off offset:576
	s_and_b64 vcc, exec, s[6:7]
	s_cbranch_vccnz .Lmy_epi_f2
	s_sleep 30
.Lmy_epi_f2:
	global_load_dwordx2 v[96:97], v[116:117], off
	global_load_dwordx4 v[80:83], v[120:121], off
	global_load_dwordx4 v[84:87], v[120:121], off offset:64
	global_load_dwordx4 v[88:91], v[120:121], off offset:512
	global_load_dwordx4 v[92:95], v[120:121], off offset:576
	v_add_u32_e32 v98, 0x80, v194
	v_lshl_add_u64 v[100:101], s[8:9], 0, v[114:115]
	v_ashrrev_i32_e32 v99, 31, v98
	v_lshl_add_u64 v[100:101], v[100:101], 0, v[160:161]
	v_lshl_add_u64 v[102:103], v[98:99], 3, s[14:15]
	v_lshlrev_b64 v[98:99], 12, v[98:99]
	v_lshl_add_u64 v[104:105], s[16:17], 0, v[98:99]
	v_lshl_add_u64 v[104:105], v[104:105], 0, v[160:161]
	s_waitcnt vmcnt(4)
	v_mul_f32_e32 v106, 0x3fb504f3, v97
	s_waitcnt vmcnt(3)
	v_sub_f32_e32 v81, v81, v96
	v_sub_f32_e32 v80, v80, v96
	v_sub_f32_e32 v83, v83, v96
	v_sub_f32_e32 v82, v82, v96
	s_waitcnt vmcnt(2)
	v_sub_f32_e32 v85, v85, v96
	v_sub_f32_e32 v84, v84, v96
	v_sub_f32_e32 v87, v87, v96
	v_sub_f32_e32 v86, v86, v96
	s_waitcnt vmcnt(1)
	v_sub_f32_e32 v89, v89, v96
	v_sub_f32_e32 v88, v88, v96
	v_sub_f32_e32 v91, v91, v96
	v_sub_f32_e32 v90, v90, v96
	s_waitcnt vmcnt(0)
	v_sub_f32_e32 v93, v93, v96
	v_sub_f32_e32 v92, v92, v96
	v_sub_f32_e32 v95, v95, v96
	v_sub_f32_e32 v94, v94, v96
	v_pk_mul_f32 v[82:83], v[82:83], v[106:107] op_sel_hi:[1,0]
	v_pk_mul_f32 v[80:81], v[80:81], v[106:107] op_sel_hi:[1,0]
	v_pk_mul_f32 v[86:87], v[86:87], v[106:107] op_sel_hi:[1,0]
	v_pk_mul_f32 v[84:85], v[84:85], v[106:107] op_sel_hi:[1,0]
	v_pk_mul_f32 v[90:91], v[106:107], v[90:91] op_sel_hi:[0,1]
	v_pk_mul_f32 v[88:89], v[106:107], v[88:89] op_sel_hi:[0,1]
	v_pk_mul_f32 v[94:95], v[106:107], v[94:95] op_sel_hi:[0,1]
	v_pk_mul_f32 v[92:93], v[106:107], v[92:93] op_sel_hi:[0,1]
	v_pk_fma_f32 v[80:81], v[140:141], v[80:81], v[186:187]
	v_pk_fma_f32 v[82:83], v[142:143], v[82:83], v[166:167]
	v_pk_fma_f32 v[84:85], v[136:137], v[84:85], v[188:189]
	v_pk_fma_f32 v[86:87], v[138:139], v[86:87], v[168:169]
	v_pk_fma_f32 v[88:89], v[132:133], v[88:89], v[190:191]
	v_pk_fma_f32 v[90:91], v[134:135], v[90:91], v[170:171]
	v_pk_fma_f32 v[92:93], v[128:129], v[92:93], v[192:193]
	v_pk_fma_f32 v[94:95], v[130:131], v[94:95], v[172:173]
	v_pk_fma_f32 v[78:79], v[78:79], v[174:175], v[82:83]
	v_pk_fma_f32 v[76:77], v[76:77], v[176:177], v[80:81]
	v_pk_fma_f32 v[74:75], v[74:75], v[178:179], v[86:87]
	v_pk_fma_f32 v[72:73], v[72:73], v[180:181], v[84:85]
	v_pk_fma_f32 v[70:71], v[70:71], v[182:183], v[90:91]
	v_pk_fma_f32 v[68:69], v[68:69], v[184:185], v[88:89]
	v_pk_fma_f32 v[66:67], v[66:67], v[162:163], v[94:95]
	v_pk_fma_f32 v[64:65], v[64:65], v[164:165], v[92:93]
	global_store_dwordx4 v[100:101], v[76:79], off
	global_store_dwordx4 v[100:101], v[72:75], off offset:64
	global_store_dwordx4 v[100:101], v[68:71], off offset:512
	global_store_dwordx4 v[100:101], v[64:67], off offset:576
	s_and_b64 vcc, exec, s[6:7]
	s_cbranch_vccnz .Lmy_epi_f3
	s_sleep 30
.Lmy_epi_f3:
	global_load_dwordx2 v[80:81], v[102:103], off
	global_load_dwordx4 v[64:67], v[104:105], off
	global_load_dwordx4 v[68:71], v[104:105], off offset:64
	global_load_dwordx4 v[72:75], v[104:105], off offset:512
	global_load_dwordx4 v[76:79], v[104:105], off offset:576
	v_add_u32_e32 v82, 0x90, v194
	v_lshl_add_u64 v[86:87], s[8:9], 0, v[98:99]
	v_ashrrev_i32_e32 v83, 31, v82
	v_lshl_add_u64 v[86:87], v[86:87], 0, v[160:161]
	v_lshl_add_u64 v[84:85], v[82:83], 3, s[14:15]
	v_lshlrev_b64 v[82:83], 12, v[82:83]
	v_lshl_add_u64 v[88:89], s[16:17], 0, v[82:83]
	v_lshl_add_u64 v[88:89], v[88:89], 0, v[160:161]
	s_waitcnt vmcnt(4)
	v_mul_f32_e32 v90, 0x3fb504f3, v81
	s_waitcnt vmcnt(3)
	v_sub_f32_e32 v65, v65, v80
	v_sub_f32_e32 v64, v64, v80
	v_sub_f32_e32 v67, v67, v80
	v_sub_f32_e32 v66, v66, v80
	s_waitcnt vmcnt(2)
	v_sub_f32_e32 v69, v69, v80
	v_sub_f32_e32 v68, v68, v80
	v_sub_f32_e32 v71, v71, v80
	v_sub_f32_e32 v70, v70, v80
	s_waitcnt vmcnt(1)
	v_sub_f32_e32 v73, v73, v80
	v_sub_f32_e32 v72, v72, v80
	v_sub_f32_e32 v75, v75, v80
	v_sub_f32_e32 v74, v74, v80
	s_waitcnt vmcnt(0)
	v_sub_f32_e32 v77, v77, v80
	v_sub_f32_e32 v76, v76, v80
	v_sub_f32_e32 v79, v79, v80
	v_sub_f32_e32 v78, v78, v80
	v_pk_mul_f32 v[66:67], v[66:67], v[90:91] op_sel_hi:[1,0]
	v_pk_mul_f32 v[64:65], v[64:65], v[90:91] op_sel_hi:[1,0]
	v_pk_mul_f32 v[70:71], v[70:71], v[90:91] op_sel_hi:[1,0]
	v_pk_mul_f32 v[68:69], v[68:69], v[90:91] op_sel_hi:[1,0]
	v_pk_mul_f32 v[74:75], v[90:91], v[74:75] op_sel_hi:[0,1]
	v_pk_mul_f32 v[72:73], v[90:91], v[72:73] op_sel_hi:[0,1]
	v_pk_mul_f32 v[78:79], v[90:91], v[78:79] op_sel_hi:[0,1]
	v_pk_mul_f32 v[76:77], v[90:91], v[76:77] op_sel_hi:[0,1]
	v_pk_fma_f32 v[64:65], v[140:141], v[64:65], v[186:187]
	v_pk_fma_f32 v[66:67], v[142:143], v[66:67], v[166:167]
	v_pk_fma_f32 v[68:69], v[136:137], v[68:69], v[188:189]
	v_pk_fma_f32 v[70:71], v[138:139], v[70:71], v[168:169]
	v_pk_fma_f32 v[72:73], v[132:133], v[72:73], v[190:191]
	v_pk_fma_f32 v[74:75], v[134:135], v[74:75], v[170:171]
	v_pk_fma_f32 v[76:77], v[128:129], v[76:77], v[192:193]
	v_pk_fma_f32 v[78:79], v[130:131], v[78:79], v[172:173]
	v_pk_fma_f32 v[62:63], v[62:63], v[174:175], v[66:67]
	v_pk_fma_f32 v[60:61], v[60:61], v[176:177], v[64:65]
	v_pk_fma_f32 v[58:59], v[58:59], v[178:179], v[70:71]
	v_pk_fma_f32 v[56:57], v[56:57], v[180:181], v[68:69]
	v_pk_fma_f32 v[54:55], v[54:55], v[182:183], v[74:75]
	v_pk_fma_f32 v[52:53], v[52:53], v[184:185], v[72:73]
	v_pk_fma_f32 v[50:51], v[50:51], v[162:163], v[78:79]
	v_pk_fma_f32 v[48:49], v[48:49], v[164:165], v[76:77]
	global_store_dwordx4 v[86:87], v[60:63], off
	global_store_dwordx4 v[86:87], v[56:59], off offset:64
	global_store_dwordx4 v[86:87], v[52:55], off offset:512
	global_store_dwordx4 v[86:87], v[48:51], off offset:576
	s_and_b64 vcc, exec, s[6:7]
	s_cbranch_vccnz .Lmy_epi_f4
	s_sleep 30
.Lmy_epi_f4:
	global_load_dwordx2 v[64:65], v[84:85], off
	global_load_dwordx4 v[48:51], v[88:89], off
	global_load_dwordx4 v[52:55], v[88:89], off offset:64
	global_load_dwordx4 v[56:59], v[88:89], off offset:512
	global_load_dwordx4 v[60:63], v[88:89], off offset:576
	v_add_u32_e32 v66, 0xa0, v194
	v_lshl_add_u64 v[70:71], s[8:9], 0, v[82:83]
	v_ashrrev_i32_e32 v67, 31, v66
	v_lshl_add_u64 v[70:71], v[70:71], 0, v[160:161]
	v_lshl_add_u64 v[68:69], v[66:67], 3, s[14:15]
	v_lshlrev_b64 v[66:67], 12, v[66:67]
	v_lshl_add_u64 v[72:73], s[16:17], 0, v[66:67]
	v_lshl_add_u64 v[72:73], v[72:73], 0, v[160:161]
	s_waitcnt vmcnt(4)
	v_mul_f32_e32 v74, 0x3fb504f3, v65
	s_waitcnt vmcnt(3)
	v_sub_f32_e32 v49, v49, v64
	v_sub_f32_e32 v48, v48, v64
	v_sub_f32_e32 v51, v51, v64
	v_sub_f32_e32 v50, v50, v64
	s_waitcnt vmcnt(2)
	v_sub_f32_e32 v53, v53, v64
	v_sub_f32_e32 v52, v52, v64
	v_sub_f32_e32 v55, v55, v64
	v_sub_f32_e32 v54, v54, v64
	s_waitcnt vmcnt(1)
	v_sub_f32_e32 v57, v57, v64
	v_sub_f32_e32 v56, v56, v64
	v_sub_f32_e32 v59, v59, v64
	v_sub_f32_e32 v58, v58, v64
	s_waitcnt vmcnt(0)
	v_sub_f32_e32 v61, v61, v64
	v_sub_f32_e32 v60, v60, v64
	v_sub_f32_e32 v63, v63, v64
	v_sub_f32_e32 v62, v62, v64
	v_pk_mul_f32 v[50:51], v[50:51], v[74:75] op_sel_hi:[1,0]
	v_pk_mul_f32 v[48:49], v[48:49], v[74:75] op_sel_hi:[1,0]
	v_pk_mul_f32 v[54:55], v[54:55], v[74:75] op_sel_hi:[1,0]
	v_pk_mul_f32 v[52:53], v[52:53], v[74:75] op_sel_hi:[1,0]
	v_pk_mul_f32 v[58:59], v[74:75], v[58:59] op_sel_hi:[0,1]
	v_pk_mul_f32 v[56:57], v[74:75], v[56:57] op_sel_hi:[0,1]
	v_pk_mul_f32 v[62:63], v[74:75], v[62:63] op_sel_hi:[0,1]
	v_pk_mul_f32 v[60:61], v[74:75], v[60:61] op_sel_hi:[0,1]
	v_pk_fma_f32 v[48:49], v[140:141], v[48:49], v[186:187]
	v_pk_fma_f32 v[50:51], v[142:143], v[50:51], v[166:167]
	v_pk_fma_f32 v[52:53], v[136:137], v[52:53], v[188:189]
	v_pk_fma_f32 v[54:55], v[138:139], v[54:55], v[168:169]
	v_pk_fma_f32 v[56:57], v[132:133], v[56:57], v[190:191]
	v_pk_fma_f32 v[58:59], v[134:135], v[58:59], v[170:171]
	v_pk_fma_f32 v[60:61], v[128:129], v[60:61], v[192:193]
	v_pk_fma_f32 v[62:63], v[130:131], v[62:63], v[172:173]
	v_pk_fma_f32 v[46:47], v[46:47], v[174:175], v[50:51]
	v_pk_fma_f32 v[44:45], v[44:45], v[176:177], v[48:49]
	v_pk_fma_f32 v[42:43], v[42:43], v[178:179], v[54:55]
	v_pk_fma_f32 v[40:41], v[40:41], v[180:181], v[52:53]
	v_pk_fma_f32 v[38:39], v[38:39], v[182:183], v[58:59]
	v_pk_fma_f32 v[36:37], v[36:37], v[184:185], v[56:57]
	v_pk_fma_f32 v[34:35], v[34:35], v[162:163], v[62:63]
	v_pk_fma_f32 v[32:33], v[32:33], v[164:165], v[60:61]
	global_store_dwordx4 v[70:71], v[44:47], off
	global_store_dwordx4 v[70:71], v[40:43], off offset:64
	global_store_dwordx4 v[70:71], v[36:39], off offset:512
	global_store_dwordx4 v[70:71], v[32:35], off offset:576
	s_and_b64 vcc, exec, s[6:7]
	s_cbranch_vccnz .Lmy_epi_f5
	s_sleep 30
.Lmy_epi_f5:
	global_load_dwordx2 v[48:49], v[68:69], off
	global_load_dwordx4 v[32:35], v[72:73], off
	global_load_dwordx4 v[36:39], v[72:73], off offset:64
	global_load_dwordx4 v[40:43], v[72:73], off offset:512
	global_load_dwordx4 v[44:47], v[72:73], off offset:576
	v_add_u32_e32 v50, 0xb0, v194
	v_lshl_add_u64 v[54:55], s[8:9], 0, v[66:67]
	v_ashrrev_i32_e32 v51, 31, v50
	v_lshl_add_u64 v[54:55], v[54:55], 0, v[160:161]
	v_lshl_add_u64 v[52:53], v[50:51], 3, s[14:15]
	v_lshlrev_b64 v[50:51], 12, v[50:51]
	v_lshl_add_u64 v[56:57], s[16:17], 0, v[50:51]
	v_lshl_add_u64 v[56:57], v[56:57], 0, v[160:161]
	s_waitcnt vmcnt(4)
	v_mul_f32_e32 v58, 0x3fb504f3, v49
	s_waitcnt vmcnt(3)
	v_sub_f32_e32 v33, v33, v48
	v_sub_f32_e32 v32, v32, v48
	v_sub_f32_e32 v35, v35, v48
	v_sub_f32_e32 v34, v34, v48
	s_waitcnt vmcnt(2)
	v_sub_f32_e32 v37, v37, v48
	v_sub_f32_e32 v36, v36, v48
	v_sub_f32_e32 v39, v39, v48
	v_sub_f32_e32 v38, v38, v48
	s_waitcnt vmcnt(1)
	v_sub_f32_e32 v41, v41, v48
	v_sub_f32_e32 v40, v40, v48
	v_sub_f32_e32 v43, v43, v48
	v_sub_f32_e32 v42, v42, v48
	s_waitcnt vmcnt(0)
	v_sub_f32_e32 v45, v45, v48
	v_sub_f32_e32 v44, v44, v48
	v_sub_f32_e32 v47, v47, v48
	v_sub_f32_e32 v46, v46, v48
	v_pk_mul_f32 v[34:35], v[34:35], v[58:59] op_sel_hi:[1,0]
	v_pk_mul_f32 v[32:33], v[32:33], v[58:59] op_sel_hi:[1,0]
	v_pk_mul_f32 v[38:39], v[38:39], v[58:59] op_sel_hi:[1,0]
	v_pk_mul_f32 v[36:37], v[36:37], v[58:59] op_sel_hi:[1,0]
	v_pk_mul_f32 v[42:43], v[58:59], v[42:43] op_sel_hi:[0,1]
	v_pk_mul_f32 v[40:41], v[58:59], v[40:41] op_sel_hi:[0,1]
	v_pk_mul_f32 v[46:47], v[58:59], v[46:47] op_sel_hi:[0,1]
	v_pk_mul_f32 v[44:45], v[58:59], v[44:45] op_sel_hi:[0,1]
	v_pk_fma_f32 v[32:33], v[140:141], v[32:33], v[186:187]
	v_pk_fma_f32 v[34:35], v[142:143], v[34:35], v[166:167]
	v_pk_fma_f32 v[36:37], v[136:137], v[36:37], v[188:189]
	v_pk_fma_f32 v[38:39], v[138:139], v[38:39], v[168:169]
	v_pk_fma_f32 v[40:41], v[132:133], v[40:41], v[190:191]
	v_pk_fma_f32 v[42:43], v[134:135], v[42:43], v[170:171]
	v_pk_fma_f32 v[44:45], v[128:129], v[44:45], v[192:193]
	v_pk_fma_f32 v[46:47], v[130:131], v[46:47], v[172:173]
	v_pk_fma_f32 v[30:31], v[30:31], v[174:175], v[34:35]
	v_pk_fma_f32 v[28:29], v[28:29], v[176:177], v[32:33]
	v_pk_fma_f32 v[26:27], v[26:27], v[178:179], v[38:39]
	v_pk_fma_f32 v[24:25], v[24:25], v[180:181], v[36:37]
	v_pk_fma_f32 v[22:23], v[22:23], v[182:183], v[42:43]
	v_pk_fma_f32 v[20:21], v[20:21], v[184:185], v[40:41]
	v_pk_fma_f32 v[18:19], v[18:19], v[162:163], v[46:47]
	v_pk_fma_f32 v[16:17], v[16:17], v[164:165], v[44:45]
	global_store_dwordx4 v[54:55], v[28:31], off
	global_store_dwordx4 v[54:55], v[24:27], off offset:64
	global_store_dwordx4 v[54:55], v[20:23], off offset:512
	global_store_dwordx4 v[54:55], v[16:19], off offset:576
	s_and_b64 vcc, exec, s[6:7]
	s_cbranch_vccnz .Lmy_epi_f6
	s_sleep 30
.Lmy_epi_f6:
	global_load_dwordx2 v[32:33], v[52:53], off
	global_load_dwordx4 v[16:19], v[56:57], off
	global_load_dwordx4 v[20:23], v[56:57], off offset:64
	global_load_dwordx4 v[24:27], v[56:57], off offset:512
	global_load_dwordx4 v[28:31], v[56:57], off offset:576
	v_lshl_add_u64 v[34:35], s[8:9], 0, v[50:51]
	v_lshl_add_u64 v[34:35], v[34:35], 0, v[160:161]
	s_waitcnt vmcnt(4)
	v_mul_f32_e32 v36, 0x3fb504f3, v33
	s_waitcnt vmcnt(3)
	v_sub_f32_e32 v17, v17, v32
	v_sub_f32_e32 v16, v16, v32
	v_sub_f32_e32 v19, v19, v32
	v_sub_f32_e32 v18, v18, v32
	s_waitcnt vmcnt(2)
	v_sub_f32_e32 v21, v21, v32
	v_sub_f32_e32 v20, v20, v32
	v_sub_f32_e32 v23, v23, v32
	v_sub_f32_e32 v22, v22, v32
	s_waitcnt vmcnt(1)
	v_sub_f32_e32 v25, v25, v32
	v_sub_f32_e32 v24, v24, v32
	v_sub_f32_e32 v27, v27, v32
	v_sub_f32_e32 v26, v26, v32
	s_waitcnt vmcnt(0)
	v_sub_f32_e32 v29, v29, v32
	v_sub_f32_e32 v28, v28, v32
	v_sub_f32_e32 v31, v31, v32
	v_sub_f32_e32 v30, v30, v32
	v_pk_mul_f32 v[18:19], v[18:19], v[36:37] op_sel_hi:[1,0]
	v_pk_mul_f32 v[16:17], v[16:17], v[36:37] op_sel_hi:[1,0]
	v_pk_mul_f32 v[22:23], v[22:23], v[36:37] op_sel_hi:[1,0]
	v_pk_mul_f32 v[20:21], v[20:21], v[36:37] op_sel_hi:[1,0]
	v_pk_mul_f32 v[26:27], v[36:37], v[26:27] op_sel_hi:[0,1]
	v_pk_mul_f32 v[24:25], v[36:37], v[24:25] op_sel_hi:[0,1]
	v_pk_mul_f32 v[30:31], v[36:37], v[30:31] op_sel_hi:[0,1]
	v_pk_mul_f32 v[28:29], v[36:37], v[28:29] op_sel_hi:[0,1]
	v_pk_fma_f32 v[16:17], v[140:141], v[16:17], v[186:187]
	v_pk_fma_f32 v[18:19], v[142:143], v[18:19], v[166:167]
	v_pk_fma_f32 v[20:21], v[136:137], v[20:21], v[188:189]
	v_pk_fma_f32 v[22:23], v[138:139], v[22:23], v[168:169]
	v_pk_fma_f32 v[24:25], v[132:133], v[24:25], v[190:191]
	v_pk_fma_f32 v[26:27], v[134:135], v[26:27], v[170:171]
	v_pk_fma_f32 v[28:29], v[128:129], v[28:29], v[192:193]
	v_pk_fma_f32 v[30:31], v[130:131], v[30:31], v[172:173]
	v_pk_fma_f32 v[14:15], v[14:15], v[174:175], v[18:19]
	v_pk_fma_f32 v[12:13], v[12:13], v[176:177], v[16:17]
	v_pk_fma_f32 v[10:11], v[10:11], v[178:179], v[22:23]
	v_pk_fma_f32 v[8:9], v[8:9], v[180:181], v[20:21]
	v_pk_fma_f32 v[6:7], v[6:7], v[182:183], v[26:27]
	v_pk_fma_f32 v[4:5], v[4:5], v[184:185], v[24:25]
	v_pk_fma_f32 v[2:3], v[2:3], v[162:163], v[30:31]
	v_pk_fma_f32 v[0:1], v[0:1], v[164:165], v[28:29]
	global_store_dwordx4 v[34:35], v[12:15], off
	global_store_dwordx4 v[34:35], v[8:11], off offset:64
	global_store_dwordx4 v[34:35], v[4:7], off offset:512
	global_store_dwordx4 v[34:35], v[0:3], off offset:576
	s_and_b64 vcc, exec, s[6:7]
	s_mov_b64 s[6:7], -1
	s_cbranch_vccnz .LBB0_1365
